# P9 epilogue: the two 8-byte ACT stores per row group merged into one 16-byte store (n=0 result parked in free registers)
# speedup vs baseline: 1.0027x; 1.0014x over previous
; __device__ __forceinline__ float sigmoidf_(float x) { return __builtin_amdgcn_rcpf(1.0f + __builtin_amdgcn_exp2f(-x * LOG2E)); }
; template <int CTRL> __device__ __forceinline__ float dpp_ror(float v) { return __builtin_bit_cast(float, __builtin_amdgcn_update_dpp(0, __builtin_bit_cast(int, v), CTRL, 0xf, 0xf, false)); }
;     __device__ __forceinline__ void operator()(const Acc& acc, const Unit& u, int wr, int wc, int fr, int fq) const {
;     ...
;         for (int n = 0; n < 2; ++n) {
;             const int j4 = u.pn * HALF + wc * 32 + 8 * fq + 4 * n;
;             const f32x4 wa0 = *(const f32x4*)(cw + j4), wa1 = *(const f32x4*)(cw + NUP + j4), wa2 = *(const f32x4*)(cw + 2 * NUP + j4), ba = *(const f32x4*)(cb + j4);
;             const f32x4 wg0 = *(const f32x4*)(cw + FF + j4), wg1 = *(const f32x4*)(cw + NUP + FF + j4), wg2 = *(const f32x4*)(cw + 2 * NUP + FF + j4), bg = *(const f32x4*)(cb + FF + j4);
;             const int rawcol = u.pn * BM + wc * 32 + 8 * fq + 4 * n;
; #pragma unroll
;             for (int ai = 0; ai < 2; ++ai) {
;                 const int gi = u.pm * 4 + ai * 2 + wr;
;                 f32x4 pa = (f32x4){0.f, 0.f, 0.f, 0.f}, pg = pa;
; #pragma unroll
;                 for (int m = 0; m < 4; ++m) {
;                     const f32x4 ca = acc[ai][0][m][n], cg = acc[ai][1][m][n];
;                     f32x4 o;
; #pragma unroll
;                     for (int e = 0; e < 4; ++e) {
;                         const float ta1 = (fr == 15) ? pa[e] : ca[e], ta2 = (fr >= 14) ? pa[e] : ca[e], tg1 = (fr == 15) ? pg[e] : cg[e], tg2 = (fr >= 14) ? pg[e] : cg[e];
;                         const float a1 = dpp_ror<0x121>(ta1), a2 = dpp_ror<0x122>(ta2), g1 = dpp_ror<0x121>(tg1), g2 = dpp_ror<0x122>(tg2);
;                         const float va = ba[e] + wa0[e] * a2 + wa1[e] * a1 + wa2[e] * ca[e];
;                         const float vg = bg[e] + wg0[e] * g2 + wg1[e] * g1 + wg2[e] * cg[e];
;                         o[e] = vg * sigmoidf_(vg) * va;
;                     }
;                     const int row = u.pm * BM + ai * HALF + wr * 64 + m * 16 + fr;
;                     if (!(m == 0 && fr < 2)) { v2u w; w.x = pk2a(o[0], o[1]); w.y = pk2a(o[2], o[3]); *(v2u*)(ACT + (size_t)row * FF + j4) = w; }
.LBB0_906:
	v_lshl_or_b32 v184, s12, 7, v217
	v_ashrrev_i32_e32 v185, 31, v184
	v_readlane_b32 s76, v253, 4
	v_lshlrev_b64 v[138:139], 2, v[184:185]
	v_readlane_b32 s78, v253, 6
	v_readlane_b32 s79, v253, 7
	v_readlane_b32 s80, v253, 8
	v_readlane_b32 s81, v253, 9
	v_lshl_add_u64 v[186:187], s[78:79], 0, v[138:139]
	v_lshl_add_u64 v[114:115], s[28:29], 0, v[138:139]
	v_lshl_add_u64 v[118:119], s[30:31], 0, v[138:139]
	v_lshl_add_u64 v[188:189], s[80:81], 0, v[138:139]
	v_lshl_add_u64 v[130:131], s[36:37], 0, v[138:139]
	v_lshl_add_u64 v[132:133], s[38:39], 0, v[138:139]
	v_lshl_add_u64 v[140:141], s[40:41], 0, v[138:139]
	v_lshl_add_u64 v[138:139], s[42:43], 0, v[138:139]
	global_load_dwordx4 v[110:113], v[186:187], off
	s_nop 0
	global_load_dwordx4 v[114:117], v[114:115], off
	s_nop 0
	global_load_dwordx4 v[126:129], v[118:119], off
	v_cndmask_b32_e64 v183, v158, 0, s[2:3]
	global_load_dwordx4 v[118:121], v[188:189], off
	global_load_dwordx4 v[134:137], v[130:131], off
	s_nop 0
	global_load_dwordx4 v[130:133], v[132:133], off
	v_mov_b32_e32 v182, 0
	global_load_dwordx4 v[142:145], v[140:141], off
	v_mov_b32_e32 v202, 0
	global_load_dwordx4 v[138:141], v[138:139], off
	v_mov_b32_dpp v182, v183 row_ror:1 row_mask:0xf bank_mask:0xf
	v_cndmask_b32_e64 v183, v158, 0, s[4:5]
	v_mov_b32_e32 v208, 0
	v_mov_b32_e32 v210, 0
	v_mov_b32_dpp v202, v183 row_ror:2 row_mask:0xf bank_mask:0xf
	v_cndmask_b32_e64 v183, v154, 0, s[2:3]
	v_mov_b32_e32 v204, 0
	v_mov_b32_e32 v206, 0
	v_mov_b32_dpp v208, v183 row_ror:1 row_mask:0xf bank_mask:0xf
	v_cndmask_b32_e64 v183, v154, 0, s[4:5]
	v_mov_b32_e32 v212, 0
	v_mov_b32_e32 v214, 0
	v_mov_b32_dpp v210, v183 row_ror:2 row_mask:0xf bank_mask:0xf
	v_cndmask_b32_e64 v183, v159, 0, s[2:3]
	v_cndmask_b32_e64 v190, v160, 0, s[2:3]
	v_mov_b32_e32 v203, 0
	v_mov_b32_dpp v204, v183 row_ror:1 row_mask:0xf bank_mask:0xf
	v_cndmask_b32_e64 v183, v159, 0, s[4:5]
	v_mov_b32_e32 v209, 0
	v_mov_b32_e32 v211, 0
	v_mov_b32_dpp v206, v183 row_ror:2 row_mask:0xf bank_mask:0xf
	v_cndmask_b32_e64 v183, v155, 0, s[2:3]
	v_mov_b32_e32 v205, 0
	v_mov_b32_e32 v207, 0
	v_mov_b32_dpp v212, v183 row_ror:1 row_mask:0xf bank_mask:0xf
	v_cndmask_b32_e64 v183, v155, 0, s[4:5]
	v_mov_b32_e32 v213, 0
	v_mov_b32_e32 v215, 0
	v_mov_b32_dpp v214, v183 row_ror:2 row_mask:0xf bank_mask:0xf
	v_mov_b32_e32 v183, 0
	v_lshl_add_u32 v220, s10, 8, v1
	v_readlane_b32 s77, v253, 5
	v_mov_b32_dpp v183, v190 row_ror:1 row_mask:0xf bank_mask:0xf
	v_cndmask_b32_e64 v190, v160, 0, s[4:5]
	v_readlane_b32 s82, v253, 10
	v_readlane_b32 s83, v253, 11
	v_mov_b32_dpp v203, v190 row_ror:2 row_mask:0xf bank_mask:0xf
	v_cndmask_b32_e64 v190, v156, 0, s[2:3]
	s_nop 1
	v_mov_b32_dpp v209, v190 row_ror:1 row_mask:0xf bank_mask:0xf
	v_cndmask_b32_e64 v190, v156, 0, s[4:5]
	s_nop 1
	v_mov_b32_dpp v211, v190 row_ror:2 row_mask:0xf bank_mask:0xf
	v_cndmask_b32_e64 v190, v161, 0, s[2:3]
	s_nop 1
	v_mov_b32_dpp v205, v190 row_ror:1 row_mask:0xf bank_mask:0xf
	v_cndmask_b32_e64 v190, v161, 0, s[4:5]
	s_nop 1
	v_mov_b32_dpp v207, v190 row_ror:2 row_mask:0xf bank_mask:0xf
	v_cndmask_b32_e64 v190, v157, 0, s[2:3]
	s_nop 1
	v_mov_b32_dpp v213, v190 row_ror:1 row_mask:0xf bank_mask:0xf
	v_cndmask_b32_e64 v190, v157, 0, s[4:5]
	s_nop 1
	v_mov_b32_dpp v215, v190 row_ror:2 row_mask:0xf bank_mask:0xf
	s_and_saveexec_b64 s[52:53], s[6:7]
	s_xor_b64 s[52:53], exec, s[52:53]
	s_cbranch_execz .LBB0_908
	s_waitcnt vmcnt(0)
	v_pk_mul_f32 v[196:197], v[156:157], v[144:145]
	v_pk_mul_f32 v[198:199], v[154:155], v[142:143]
	v_mov_b32_e32 v222, v135
	v_mov_b32_e32 v223, v137
	v_mov_b32_e32 v224, v139
	v_mov_b32_e32 v225, v141
	v_mov_b32_e32 v200, v199
	v_mov_b32_e32 v201, v197
	v_mov_b32_e32 v199, v196
	v_mov_b32_e32 v196, v131
	v_mov_b32_e32 v197, v133
	v_pk_fma_f32 v[214:215], v[222:223], v[214:215], v[224:225]
	v_pk_mul_f32 v[190:191], v[160:161], v[128:129]
	v_pk_fma_f32 v[196:197], v[196:197], v[212:213], v[214:215]
	v_mov_b32_e32 v212, v134
	v_mov_b32_e32 v213, v136
	v_mov_b32_e32 v214, v138
	v_mov_b32_e32 v215, v140
	v_pk_add_f32 v[196:197], v[200:201], v[196:197]
	v_mov_b32_e32 v200, v130
	v_mov_b32_e32 v201, v132
	v_pk_fma_f32 v[210:211], v[212:213], v[210:211], v[214:215]
	v_pk_mul_f32 v[192:193], v[158:159], v[126:127]
	v_pk_fma_f32 v[200:201], v[200:201], v[208:209], v[210:211]
	v_mov_b32_e32 v195, v191
	v_mul_f32_e32 v191, 0xbfb8aa3b, v197
	v_pk_add_f32 v[198:199], v[198:199], v[200:201]
	v_mov_b32_e32 v194, v193
	v_exp_f32_e32 v191, v191
	v_mul_f32_e32 v193, 0xbfb8aa3b, v199
	v_exp_f32_e32 v200, v193
	v_mov_b32_e32 v193, v190
	v_add_f32_e32 v190, 1.0, v191
	v_rcp_f32_e32 v191, v190
	v_add_f32_e32 v190, 1.0, v200
	v_rcp_f32_e32 v201, v190
	v_mul_f32_e32 v190, 0xbfb8aa3b, v196
	v_exp_f32_e32 v190, v190
	v_mov_b32_e32 v210, v111
	v_mov_b32_e32 v211, v113
	v_mov_b32_e32 v212, v119
	v_add_f32_e32 v190, 1.0, v190
	v_rcp_f32_e32 v190, v190
	v_mov_b32_e32 v213, v121
	v_mov_b32_e32 v208, v115
	v_mov_b32_e32 v209, v117
	v_pk_mul_f32 v[190:191], v[196:197], v[190:191]
	v_mul_f32_e32 v197, 0xbfb8aa3b, v198
	v_exp_f32_e32 v200, v197
	v_pk_fma_f32 v[206:207], v[210:211], v[206:207], v[212:213]
	v_mov_b32_e32 v196, v110
	v_pk_fma_f32 v[204:205], v[208:209], v[204:205], v[206:207]
	v_add_f32_e32 v200, 1.0, v200
	v_rcp_f32_e32 v200, v200
	v_pk_add_f32 v[194:195], v[194:195], v[204:205]
	v_mov_b32_e32 v197, v112
	v_mov_b32_e32 v204, v118
	v_mov_b32_e32 v205, v120
	v_pk_mul_f32 v[190:191], v[194:195], v[190:191]
	v_mov_b32_e32 v194, v114
	v_mov_b32_e32 v195, v116
	v_pk_fma_f32 v[196:197], v[196:197], v[202:203], v[204:205]
	v_add_u32_e32 v191, 0x10000, v191
	v_pk_fma_f32 v[182:183], v[194:195], v[182:183], v[196:197]
	v_add_u32_e32 v190, 0x10000, v190
	v_pk_add_f32 v[182:183], v[192:193], v[182:183]
	v_pk_mul_f32 v[192:193], v[198:199], v[200:201]
	v_and_b32_e32 v191, 0xfffe0000, v191
	v_pk_mul_f32 v[182:183], v[182:183], v[192:193]
	v_and_b32_e32 v190, 0xfffe0000, v190
	v_add_u32_e32 v182, 0x10000, v182
	v_add_u32_e32 v183, 0x10000, v183
	v_and_b32_sdwa v183, v183, s72 dst_sel:DWORD dst_unused:UNUSED_PAD src0_sel:WORD_1 src1_sel:DWORD
	v_and_b32_sdwa v182, v182, s72 dst_sel:DWORD dst_unused:UNUSED_PAD src0_sel:WORD_1 src1_sel:DWORD
	v_or_b32_e32 v183, v191, v183
	v_or_b32_e32 v182, v190, v182
	v_mov_b64_e32 v[190:191], s[20:21]
	v_mad_i64_i32 v[190:191], s[54:55], v220, s70, v[190:191]
	v_lshl_add_u64 v[190:191], v[184:185], 1, v[190:191]
	v_mov_b32_e32 v238, v182
	v_mov_b32_e32 v239, v183
	v_mov_b32_e32 v193, v133
	v_mov_b32_e32 v192, v131
	v_mov_b32_e32 v197, v137
	v_mov_b32_e32 v196, v135
	v_mov_b32_e32 v201, v141
	v_mov_b32_e32 v200, v139
	v_mov_b32_e32 v131, v132
	v_mov_b32_e32 v135, v136
	v_mov_b32_e32 v139, v140
	v_mov_b32_e32 v191, v117
	v_mov_b32_e32 v190, v115
	v_mov_b32_e32 v195, v113
	v_mov_b32_e32 v194, v111
	v_mov_b32_e32 v199, v121
	v_mov_b32_e32 v198, v119
	v_mov_b32_e32 v115, v116
	v_mov_b32_e32 v111, v112
	v_mov_b32_e32 v119, v120

; __device__ __forceinline__ float sigmoidf_(float x) { return __builtin_amdgcn_rcpf(1.0f + __builtin_amdgcn_exp2f(-x * LOG2E)); }
; template <int CTRL> __device__ __forceinline__ float dpp_ror(float v) { return __builtin_bit_cast(float, __builtin_amdgcn_update_dpp(0, __builtin_bit_cast(int, v), CTRL, 0xf, 0xf, false)); }
;     __device__ __forceinline__ void operator()(const Acc& acc, const Unit& u, int wr, int wc, int fr, int fq) const {
;     ...
;                 for (int m = 0; m < 4; ++m) {
;                     const f32x4 ca = acc[ai][0][m][n], cg = acc[ai][1][m][n];
;                     f32x4 o;
; #pragma unroll
;                     for (int e = 0; e < 4; ++e) {
;                         const float ta1 = (fr == 15) ? pa[e] : ca[e], ta2 = (fr >= 14) ? pa[e] : ca[e], tg1 = (fr == 15) ? pg[e] : cg[e], tg2 = (fr >= 14) ? pg[e] : cg[e];
;                         const float a1 = dpp_ror<0x121>(ta1), a2 = dpp_ror<0x122>(ta2), g1 = dpp_ror<0x121>(tg1), g2 = dpp_ror<0x122>(tg2);
;                         const float va = ba[e] + wa0[e] * a2 + wa1[e] * a1 + wa2[e] * ca[e];
;                         const float vg = bg[e] + wg0[e] * g2 + wg1[e] * g1 + wg2[e] * cg[e];
;                         o[e] = vg * sigmoidf_(vg) * va;
;                     }
;                     const int row = u.pm * BM + ai * HALF + wr * 64 + m * 16 + fr;
;                     if (!(m == 0 && fr < 2)) { v2u w; w.x = pk2a(o[0], o[1]); w.y = pk2a(o[2], o[3]); *(v2u*)(ACT + (size_t)row * FF + j4) = w; }
.LBB0_910:
	s_or_b64 exec, exec, s[52:53]
	s_waitcnt vmcnt(0)
	v_cndmask_b32_e64 v113, v150, v158, s[2:3]
	v_cndmask_b32_e64 v117, v150, v158, s[4:5]
	v_mov_b32_e32 v112, 0
	v_mov_b32_e32 v116, 0
	v_cndmask_b32_e64 v121, v146, v154, s[2:3]
	v_mov_b32_dpp v112, v113 row_ror:1 row_mask:0xf bank_mask:0xf
	v_mov_b32_dpp v116, v117 row_ror:2 row_mask:0xf bank_mask:0xf
	v_mov_b32_e32 v120, 0
	v_cndmask_b32_e64 v113, v151, v159, s[2:3]
	v_cndmask_b32_e64 v117, v151, v159, s[4:5]
	v_mov_b32_e32 v136, 0
	v_mov_b32_e32 v140, 0
	v_cndmask_b32_e64 v133, v146, v154, s[4:5]
	v_mov_b32_dpp v120, v121 row_ror:1 row_mask:0xf bank_mask:0xf
	v_mov_b32_e32 v132, 0
	v_cndmask_b32_e64 v121, v147, v155, s[2:3]
	v_mov_b32_dpp v136, v113 row_ror:1 row_mask:0xf bank_mask:0xf
	v_mov_b32_dpp v140, v117 row_ror:2 row_mask:0xf bank_mask:0xf
	v_mov_b32_e32 v154, 0
	v_cndmask_b32_e64 v117, v152, v160, s[2:3]
	v_mov_b32_e32 v113, 0
	v_mov_b32_dpp v132, v133 row_ror:2 row_mask:0xf bank_mask:0xf
	v_cndmask_b32_e64 v133, v147, v155, s[4:5]
	v_mov_b32_dpp v154, v121 row_ror:1 row_mask:0xf bank_mask:0xf
	v_mov_b32_e32 v158, 0
	v_cndmask_b32_e64 v121, v152, v160, s[4:5]
	v_mov_b32_dpp v113, v117 row_ror:1 row_mask:0xf bank_mask:0xf
	v_mov_b32_e32 v117, 0
	v_mov_b32_dpp v158, v133 row_ror:2 row_mask:0xf bank_mask:0xf
	v_cndmask_b32_e64 v133, v148, v156, s[2:3]
	v_mov_b32_dpp v117, v121 row_ror:2 row_mask:0xf bank_mask:0xf
	v_mov_b32_e32 v121, 0
	v_cndmask_b32_e64 v137, v148, v156, s[4:5]
	v_cndmask_b32_e64 v141, v153, v161, s[2:3]
	v_mov_b32_dpp v121, v133 row_ror:1 row_mask:0xf bank_mask:0xf
	v_mov_b32_e32 v133, 0
	v_cndmask_b32_e64 v155, v153, v161, s[4:5]
	v_cndmask_b32_e64 v156, v149, v157, s[2:3]
	v_mov_b32_dpp v133, v137 row_ror:2 row_mask:0xf bank_mask:0xf
	v_mov_b32_e32 v137, 0
	v_cndmask_b32_e64 v157, v149, v157, s[4:5]
	v_mov_b32_e32 v159, 0
	v_mov_b32_dpp v137, v141 row_ror:1 row_mask:0xf bank_mask:0xf
	v_mov_b32_e32 v141, 0
	v_mov_b32_dpp v159, v157 row_ror:2 row_mask:0xf bank_mask:0xf
	v_pk_mul_f32 v[160:161], v[146:147], v[142:143]
	v_mov_b32_dpp v141, v155 row_ror:2 row_mask:0xf bank_mask:0xf
	v_mov_b32_e32 v155, 0
	v_pk_fma_f32 v[132:133], v[134:135], v[132:133], v[138:139]
	v_mov_b32_e32 v204, v161
	v_mov_b32_dpp v155, v156 row_ror:1 row_mask:0xf bank_mask:0xf
	v_pk_mul_f32 v[156:157], v[148:149], v[144:145]
	v_pk_fma_f32 v[158:159], v[196:197], v[158:159], v[200:201]
	v_mov_b32_e32 v161, v156
	v_pk_fma_f32 v[120:121], v[130:131], v[120:121], v[132:133]
	v_mov_b32_e32 v205, v157
	v_pk_fma_f32 v[154:155], v[192:193], v[154:155], v[158:159]
	v_pk_add_f32 v[120:121], v[160:161], v[120:121]
	v_pk_add_f32 v[154:155], v[204:205], v[154:155]
	v_mul_f32_e32 v132, 0xbfb8aa3b, v121
	v_mul_f32_e32 v157, 0xbfb8aa3b, v155
	v_exp_f32_e32 v132, v132
	v_exp_f32_e32 v157, v157
	v_pk_fma_f32 v[140:141], v[194:195], v[140:141], v[198:199]
	v_pk_mul_f32 v[158:159], v[152:153], v[128:129]
	v_add_f32_e32 v132, 1.0, v132
	v_add_f32_e32 v133, 1.0, v157
	v_rcp_f32_e32 v157, v132
	v_mul_f32_e32 v132, 0xbfb8aa3b, v154
	v_exp_f32_e32 v132, v132
	v_rcp_f32_e32 v133, v133
	v_pk_fma_f32 v[136:137], v[190:191], v[136:137], v[140:141]
	v_mul_f32_e32 v140, 0xbfb8aa3b, v120
	v_add_f32_e32 v132, 1.0, v132
	v_rcp_f32_e32 v132, v132
	v_exp_f32_e32 v140, v140
	v_pk_mul_f32 v[160:161], v[150:151], v[126:127]
	v_mov_b32_e32 v205, v159
	v_mov_b32_e32 v204, v161
	v_pk_add_f32 v[136:137], v[204:205], v[136:137]
	v_pk_mul_f32 v[132:133], v[154:155], v[132:133]
	v_pk_fma_f32 v[116:117], v[110:111], v[116:117], v[118:119]
	v_pk_mul_f32 v[132:133], v[136:137], v[132:133]
	v_add_f32_e32 v136, 1.0, v140
	v_rcp_f32_e32 v156, v136
	v_mov_b32_e32 v161, v158
	v_pk_fma_f32 v[112:113], v[114:115], v[112:113], v[116:117]
	v_or_b32_e32 v203, 16, v220
	v_pk_add_f32 v[112:113], v[160:161], v[112:113]
	v_pk_mul_f32 v[116:117], v[120:121], v[156:157]
	v_cndmask_b32_e64 v137, v122, v150, s[4:5]
	v_pk_mul_f32 v[112:113], v[112:113], v[116:117]
	v_add_u32_e32 v116, 0x10000, v133
	v_add_u32_e32 v112, 0x10000, v112
	v_add_u32_e32 v113, 0x10000, v113
	v_add_u32_e32 v117, 0x10000, v132
	v_and_b32_e32 v116, 0xfffe0000, v116
	v_and_b32_e32 v120, 0xfffe0000, v117
	v_and_b32_sdwa v113, v113, s72 dst_sel:DWORD dst_unused:UNUSED_PAD src0_sel:WORD_1 src1_sel:DWORD
	v_and_b32_sdwa v112, v112, s72 dst_sel:DWORD dst_unused:UNUSED_PAD src0_sel:WORD_1 src1_sel:DWORD
	v_mov_b64_e32 v[132:133], s[20:21]
	v_or_b32_e32 v117, v116, v113
	v_or_b32_e32 v116, v120, v112
	v_mad_i64_i32 v[112:113], s[52:53], v203, s70, v[132:133]
	v_lshlrev_b64 v[120:121], 1, v[184:185]
	v_lshl_add_u64 v[112:113], v[112:113], 0, v[120:121]
	v_mov_b32_e32 v240, v116
	v_mov_b32_e32 v241, v117
	v_cndmask_b32_e64 v117, v122, v150, s[2:3]
	v_cndmask_b32_e64 v141, v106, v146, s[2:3]
	v_cndmask_b32_e64 v150, v106, v146, s[4:5]
	v_mov_b32_e32 v116, 0
	v_mov_b32_e32 v136, 0
	v_mov_b32_e32 v146, 0
	v_mov_b32_dpp v116, v117 row_ror:1 row_mask:0xf bank_mask:0xf
	v_mov_b32_dpp v136, v137 row_ror:2 row_mask:0xf bank_mask:0xf
	v_mov_b32_e32 v140, 0
	v_mov_b32_dpp v146, v150 row_ror:2 row_mask:0xf bank_mask:0xf
	v_cndmask_b32_e64 v117, v123, v151, s[2:3]
	v_cndmask_b32_e64 v137, v123, v151, s[4:5]
	v_mov_b32_e32 v150, 0
	v_mov_b32_e32 v154, 0
	v_mov_b32_dpp v140, v141 row_ror:1 row_mask:0xf bank_mask:0xf
	v_cndmask_b32_e64 v141, v107, v147, s[2:3]
	v_mov_b32_dpp v150, v117 row_ror:1 row_mask:0xf bank_mask:0xf
	v_mov_b32_dpp v154, v137 row_ror:2 row_mask:0xf bank_mask:0xf
	v_mov_b32_e32 v156, 0
	v_cndmask_b32_e64 v137, v124, v152, s[2:3]
	v_mov_b32_e32 v117, 0
	v_cndmask_b32_e64 v147, v107, v147, s[4:5]
	v_mov_b32_dpp v156, v141 row_ror:1 row_mask:0xf bank_mask:0xf
	v_mov_b32_e32 v158, 0
; __device__ __forceinline__ float sigmoidf_(float x) { return __builtin_amdgcn_rcpf(1.0f + __builtin_amdgcn_exp2f(-x * LOG2E)); }
; template <int CTRL> __device__ __forceinline__ float dpp_ror(float v) { return __builtin_bit_cast(float, __builtin_amdgcn_update_dpp(0, __builtin_bit_cast(int, v), CTRL, 0xf, 0xf, false)); }
;     __device__ __forceinline__ void operator()(const Acc& acc, const Unit& u, int wr, int wc, int fr, int fq) const {
;     ...
;                 for (int m = 0; m < 4; ++m) {
;                     const f32x4 ca = acc[ai][0][m][n], cg = acc[ai][1][m][n];
;                     f32x4 o;
; #pragma unroll
;                     for (int e = 0; e < 4; ++e) {
;                         const float ta1 = (fr == 15) ? pa[e] : ca[e], ta2 = (fr >= 14) ? pa[e] : ca[e], tg1 = (fr == 15) ? pg[e] : cg[e], tg2 = (fr >= 14) ? pg[e] : cg[e];
;                         const float a1 = dpp_ror<0x121>(ta1), a2 = dpp_ror<0x122>(ta2), g1 = dpp_ror<0x121>(tg1), g2 = dpp_ror<0x122>(tg2);
;                         const float va = ba[e] + wa0[e] * a2 + wa1[e] * a1 + wa2[e] * ca[e];
;                         const float vg = bg[e] + wg0[e] * g2 + wg1[e] * g1 + wg2[e] * cg[e];
;                         o[e] = vg * sigmoidf_(vg) * va;
;                     }
;                     const int row = u.pm * BM + ai * HALF + wr * 64 + m * 16 + fr;
;                     if (!(m == 0 && fr < 2)) { v2u w; w.x = pk2a(o[0], o[1]); w.y = pk2a(o[2], o[3]); *(v2u*)(ACT + (size_t)row * FF + j4) = w; }
	v_cndmask_b32_e64 v141, v124, v152, s[4:5]
	v_mov_b32_dpp v117, v137 row_ror:1 row_mask:0xf bank_mask:0xf
	v_mov_b32_e32 v137, 0
	v_mov_b32_dpp v158, v147 row_ror:2 row_mask:0xf bank_mask:0xf
	v_cndmask_b32_e64 v147, v108, v148, s[2:3]
	v_mov_b32_dpp v137, v141 row_ror:2 row_mask:0xf bank_mask:0xf
	v_mov_b32_e32 v141, 0
	v_cndmask_b32_e64 v148, v108, v148, s[4:5]
	v_cndmask_b32_e64 v152, v125, v153, s[4:5]
	v_mov_b32_dpp v141, v147 row_ror:1 row_mask:0xf bank_mask:0xf
	v_mov_b32_e32 v147, 0
	v_mov_b32_e32 v151, 0
	v_mov_b32_e32 v155, 0
	v_mov_b32_dpp v147, v148 row_ror:2 row_mask:0xf bank_mask:0xf
	v_cndmask_b32_e64 v148, v125, v153, s[2:3]
	v_cndmask_b32_e64 v153, v109, v149, s[2:3]
	v_cndmask_b32_e64 v149, v109, v149, s[4:5]
	v_mov_b32_e32 v157, 0
	v_mov_b32_e32 v159, 0
	v_mov_b32_dpp v151, v148 row_ror:1 row_mask:0xf bank_mask:0xf
	v_mov_b32_dpp v155, v152 row_ror:2 row_mask:0xf bank_mask:0xf
	v_mov_b32_dpp v157, v153 row_ror:1 row_mask:0xf bank_mask:0xf
	v_mov_b32_dpp v159, v149 row_ror:2 row_mask:0xf bank_mask:0xf
	v_pk_mul_f32 v[148:149], v[108:109], v[144:145]
	v_pk_mul_f32 v[152:153], v[106:107], v[142:143]
	v_pk_fma_f32 v[146:147], v[134:135], v[146:147], v[138:139]
	v_mov_b32_e32 v160, v153
	v_pk_fma_f32 v[158:159], v[196:197], v[158:159], v[200:201]
	v_mov_b32_e32 v153, v148
	v_pk_fma_f32 v[140:141], v[130:131], v[140:141], v[146:147]
	v_mov_b32_e32 v161, v149
	v_pk_fma_f32 v[156:157], v[192:193], v[156:157], v[158:159]
	v_pk_add_f32 v[140:141], v[152:153], v[140:141]
	v_pk_add_f32 v[156:157], v[160:161], v[156:157]
	v_mul_f32_e32 v146, 0xbfb8aa3b, v141
	v_mul_f32_e32 v149, 0xbfb8aa3b, v157
	v_exp_f32_e32 v146, v146
	v_exp_f32_e32 v149, v149
	v_mul_f32_e32 v148, 0xbfb8aa3b, v140
	v_exp_f32_e32 v148, v148
	v_add_f32_e32 v146, 1.0, v146
	v_add_f32_e32 v147, 1.0, v149
	v_rcp_f32_e32 v149, v146
	v_mul_f32_e32 v146, 0xbfb8aa3b, v156
	v_exp_f32_e32 v146, v146
	v_add_f32_e32 v148, 1.0, v148
	v_rcp_f32_e32 v147, v147
	v_rcp_f32_e32 v148, v148
	v_add_f32_e32 v146, 1.0, v146
	v_rcp_f32_e32 v146, v146
	v_pk_mul_f32 v[152:153], v[124:125], v[128:129]
	v_pk_mul_f32 v[158:159], v[122:123], v[126:127]
	v_pk_fma_f32 v[154:155], v[194:195], v[154:155], v[198:199]
	v_pk_fma_f32 v[136:137], v[110:111], v[136:137], v[118:119]
	v_mov_b32_e32 v160, v159
	v_mov_b32_e32 v161, v153
	v_pk_fma_f32 v[150:151], v[190:191], v[150:151], v[154:155]
	v_mov_b32_e32 v159, v152
	v_pk_fma_f32 v[116:117], v[114:115], v[116:117], v[136:137]
	v_pk_add_f32 v[150:151], v[160:161], v[150:151]
	v_pk_mul_f32 v[146:147], v[156:157], v[146:147]
	v_pk_add_f32 v[116:117], v[158:159], v[116:117]
	v_pk_mul_f32 v[136:137], v[140:141], v[148:149]
	v_pk_mul_f32 v[146:147], v[150:151], v[146:147]
	v_pk_mul_f32 v[116:117], v[116:117], v[136:137]
	v_add_u32_e32 v136, 0x10000, v147
	v_add_u32_e32 v116, 0x10000, v116
	v_add_u32_e32 v117, 0x10000, v117
	v_add_u32_e32 v137, 0x10000, v146
	v_or_b32_e32 v203, 32, v220
	v_and_b32_e32 v136, 0xfffe0000, v136
	v_and_b32_e32 v140, 0xfffe0000, v137
	v_and_b32_sdwa v117, v117, s72 dst_sel:DWORD dst_unused:UNUSED_PAD src0_sel:WORD_1 src1_sel:DWORD
	v_and_b32_sdwa v116, v116, s72 dst_sel:DWORD dst_unused:UNUSED_PAD src0_sel:WORD_1 src1_sel:DWORD
	v_or_b32_e32 v137, v136, v117
	v_or_b32_e32 v136, v140, v116
	v_mad_i64_i32 v[116:117], s[52:53], v203, s70, v[132:133]
	v_lshl_add_u64 v[116:117], v[116:117], 0, v[120:121]
	v_mov_b32_e32 v242, v136
	v_mov_b32_e32 v243, v137
	v_cndmask_b32_e64 v136, v102, v122, s[2:3]
	v_cndmask_b32_e64 v140, v98, v106, s[2:3]
	v_cndmask_b32_e64 v141, v98, v106, s[4:5]
	v_mov_b32_e32 v106, 0
	v_cndmask_b32_e64 v137, v102, v122, s[4:5]
	v_mov_b32_e32 v122, 0
	v_mov_b32_dpp v106, v136 row_ror:1 row_mask:0xf bank_mask:0xf
	v_mov_b32_e32 v136, 0
	v_mov_b32_dpp v122, v137 row_ror:2 row_mask:0xf bank_mask:0xf
	v_cndmask_b32_e64 v137, v103, v123, s[2:3]
	v_mov_b32_dpp v136, v140 row_ror:1 row_mask:0xf bank_mask:0xf
	v_mov_b32_e32 v140, 0
	v_cndmask_b32_e64 v123, v103, v123, s[4:5]
	v_mov_b32_e32 v146, 0
	v_mov_b32_dpp v140, v141 row_ror:2 row_mask:0xf bank_mask:0xf
	v_cndmask_b32_e64 v141, v99, v107, s[2:3]
	v_cndmask_b32_e64 v107, v99, v107, s[4:5]
	v_mov_b32_e32 v148, 0
	v_mov_b32_e32 v150, 0
	v_mov_b32_e32 v152, 0
	v_mov_b32_dpp v146, v137 row_ror:1 row_mask:0xf bank_mask:0xf
	v_mov_b32_dpp v148, v123 row_ror:2 row_mask:0xf bank_mask:0xf
	v_mov_b32_dpp v150, v141 row_ror:1 row_mask:0xf bank_mask:0xf
	v_mov_b32_dpp v152, v107 row_ror:2 row_mask:0xf bank_mask:0xf
	v_cndmask_b32_e64 v123, v104, v124, s[2:3]
	v_cndmask_b32_e64 v141, v100, v108, s[2:3]
	v_mov_b32_e32 v107, 0
	v_mov_b32_e32 v137, 0
	v_cndmask_b32_e64 v124, v104, v124, s[4:5]
	v_cndmask_b32_e64 v108, v100, v108, s[4:5]
	v_mov_b32_dpp v107, v123 row_ror:1 row_mask:0xf bank_mask:0xf
	v_mov_b32_e32 v123, 0
	v_mov_b32_dpp v137, v141 row_ror:1 row_mask:0xf bank_mask:0xf
	v_mov_b32_e32 v141, 0
	v_mov_b32_dpp v123, v124 row_ror:2 row_mask:0xf bank_mask:0xf
	v_cndmask_b32_e64 v124, v105, v125, s[4:5]
	v_mov_b32_dpp v141, v108 row_ror:2 row_mask:0xf bank_mask:0xf
	v_cndmask_b32_e64 v108, v105, v125, s[2:3]
	v_cndmask_b32_e64 v125, v101, v109, s[2:3]
	v_cndmask_b32_e64 v109, v101, v109, s[4:5]
	v_mov_b32_e32 v153, 0
	v_mov_b32_e32 v147, 0
	v_mov_b32_e32 v149, 0
	v_mov_b32_e32 v151, 0
	v_mov_b32_dpp v153, v109 row_ror:2 row_mask:0xf bank_mask:0xf
	v_mov_b32_dpp v147, v108 row_ror:1 row_mask:0xf bank_mask:0xf
	v_mov_b32_dpp v149, v124 row_ror:2 row_mask:0xf bank_mask:0xf
	v_mov_b32_dpp v151, v125 row_ror:1 row_mask:0xf bank_mask:0xf
	v_pk_mul_f32 v[108:109], v[100:101], v[144:145]
	v_pk_mul_f32 v[124:125], v[98:99], v[142:143]
	v_pk_fma_f32 v[152:153], v[196:197], v[152:153], v[200:201]
; __device__ __forceinline__ unsigned pk2(float lo, float hi) { unsigned r; asm("v_cvt_pk_bf16_f32 %0, %1, %2" : "=v"(r) : "v"(lo), "v"(hi)); return r; }
; __device__ __forceinline__ float sigmoidf_(float x) { return __builtin_amdgcn_rcpf(1.0f + __builtin_amdgcn_exp2f(-x * LOG2E)); }
; template <int CTRL> __device__ __forceinline__ float dpp_ror(float v) { return __builtin_bit_cast(float, __builtin_amdgcn_update_dpp(0, __builtin_bit_cast(int, v), CTRL, 0xf, 0xf, false)); }
;     __device__ __forceinline__ void operator()(const Acc& acc, const Unit& u, int wr, int wc, int fr, int fq) const {
;     ...
;                 for (int m = 0; m < 4; ++m) {
;                     const f32x4 ca = acc[ai][0][m][n], cg = acc[ai][1][m][n];
;                     f32x4 o;
; #pragma unroll
;                     for (int e = 0; e < 4; ++e) {
;                         const float ta1 = (fr == 15) ? pa[e] : ca[e], ta2 = (fr >= 14) ? pa[e] : ca[e], tg1 = (fr == 15) ? pg[e] : cg[e], tg2 = (fr >= 14) ? pg[e] : cg[e];
;                         const float a1 = dpp_ror<0x121>(ta1), a2 = dpp_ror<0x122>(ta2), g1 = dpp_ror<0x121>(tg1), g2 = dpp_ror<0x122>(tg2);
;                         const float va = ba[e] + wa0[e] * a2 + wa1[e] * a1 + wa2[e] * ca[e];
;                         const float vg = bg[e] + wg0[e] * g2 + wg1[e] * g1 + wg2[e] * cg[e];
;                         o[e] = vg * sigmoidf_(vg) * va;
;                     }
;                     const int row = u.pm * BM + ai * HALF + wr * 64 + m * 16 + fr;
;                     if (!(m == 0 && fr < 2)) { v2u w; w.x = pk2a(o[0], o[1]); w.y = pk2a(o[2], o[3]); *(v2u*)(ACT + (size_t)row * FF + j4) = w; }
;                     if ((m == 0 && fr < 2) || (m == 3 && fr >= 14)) {
;                         const int slot = (m == 0) ? fr : fr - 12;
;                         bf16* rp = RAW + ((size_t)gi * 4 + slot) * NUP + rawcol;
;                         v2u w; w.x = pk2(ca[0], ca[1]); w.y = pk2(ca[2], ca[3]); *(v2u*)rp = w;
;                         w.x = pk2(cg[0], cg[1]); w.y = pk2(cg[2], cg[3]); *(v2u*)(rp + HALF) = w;
;                     }
	v_mov_b32_e32 v154, v125
	v_mov_b32_e32 v155, v109
	v_pk_fma_f32 v[150:151], v[192:193], v[150:151], v[152:153]
	v_mov_b32_e32 v125, v108
	v_pk_add_f32 v[150:151], v[154:155], v[150:151]
	v_pk_fma_f32 v[148:149], v[194:195], v[148:149], v[198:199]
	v_mul_f32_e32 v109, 0xbfb8aa3b, v151
	v_exp_f32_e32 v152, v109
	v_pk_fma_f32 v[108:109], v[134:135], v[140:141], v[138:139]
	v_pk_mul_f32 v[140:141], v[104:105], v[128:129]
	v_pk_fma_f32 v[108:109], v[130:131], v[136:137], v[108:109]
	v_pk_fma_f32 v[122:123], v[110:111], v[122:123], v[118:119]
	v_pk_add_f32 v[108:109], v[124:125], v[108:109]
	v_add_f32_e32 v125, 1.0, v152
	v_mul_f32_e32 v124, 0xbfb8aa3b, v109
	v_exp_f32_e32 v124, v124
	v_mul_f32_e32 v136, 0xbfb8aa3b, v108
	v_exp_f32_e32 v136, v136
	v_rcp_f32_e32 v125, v125
	v_add_f32_e32 v124, 1.0, v124
	v_rcp_f32_e32 v137, v124
	v_mul_f32_e32 v124, 0xbfb8aa3b, v150
	v_exp_f32_e32 v124, v124
	v_add_f32_e32 v136, 1.0, v136
	v_rcp_f32_e32 v136, v136
	v_pk_mul_f32 v[152:153], v[102:103], v[126:127]
	v_add_f32_e32 v124, 1.0, v124
	v_rcp_f32_e32 v124, v124
	v_mov_b32_e32 v154, v153
	v_mov_b32_e32 v155, v141
	v_pk_fma_f32 v[146:147], v[190:191], v[146:147], v[148:149]
	v_mov_b32_e32 v153, v140
	v_pk_fma_f32 v[106:107], v[114:115], v[106:107], v[122:123]
	v_pk_add_f32 v[146:147], v[154:155], v[146:147]
	v_pk_mul_f32 v[124:125], v[150:151], v[124:125]
	v_pk_add_f32 v[106:107], v[152:153], v[106:107]
	v_pk_mul_f32 v[108:109], v[108:109], v[136:137]
	v_pk_mul_f32 v[124:125], v[146:147], v[124:125]
	v_pk_mul_f32 v[106:107], v[106:107], v[108:109]
	v_add_u32_e32 v108, 0x10000, v125
	v_add_u32_e32 v106, 0x10000, v106
	v_add_u32_e32 v107, 0x10000, v107
	v_add_u32_e32 v109, 0x10000, v124
	v_or_b32_e32 v156, 48, v220
	v_and_b32_e32 v108, 0xfffe0000, v108
	v_and_b32_e32 v109, 0xfffe0000, v109
	v_and_b32_sdwa v107, v107, s72 dst_sel:DWORD dst_unused:UNUSED_PAD src0_sel:WORD_1 src1_sel:DWORD
	v_and_b32_sdwa v106, v106, s72 dst_sel:DWORD dst_unused:UNUSED_PAD src0_sel:WORD_1 src1_sel:DWORD
	v_or_b32_e32 v107, v108, v107
	v_or_b32_e32 v106, v109, v106
	v_mad_i64_i32 v[108:109], s[52:53], v156, s70, v[132:133]
	v_lshl_add_u64 v[108:109], v[108:109], 0, v[120:121]
	v_mov_b32_e32 v244, v106
	v_mov_b32_e32 v245, v107
	v_lshl_add_u64 v[106:107], s[10:11], 0, v[172:173]
	s_and_saveexec_b64 s[52:53], s[4:5]
	s_cbranch_execz .LBB0_912
	v_mov_b64_e32 v[122:123], s[0:1]
	v_mad_u64_u32 v[122:123], s[54:55], v106, s71, v[122:123]
	v_mad_i32_i24 v123, v107, s71, v123
	v_lshl_add_u64 v[122:123], v[182:183], 1, v[122:123]
	v_cvt_pk_bf16_f32 v102, v102, v103
	v_cvt_pk_bf16_f32 v103, v104, v105
	global_store_dwordx2 v[122:123], v[102:103], off
	v_cvt_pk_bf16_f32 v98, v98, v99
	v_cvt_pk_bf16_f32 v99, v100, v101
	global_store_dwordx2 v[122:123], v[98:99], off offset:256
; __device__ __forceinline__ float sigmoidf_(float x) { return __builtin_amdgcn_rcpf(1.0f + __builtin_amdgcn_exp2f(-x * LOG2E)); }
; template <int CTRL> __device__ __forceinline__ float dpp_ror(float v) { return __builtin_bit_cast(float, __builtin_amdgcn_update_dpp(0, __builtin_bit_cast(int, v), CTRL, 0xf, 0xf, false)); }
;     __device__ __forceinline__ void operator()(const Acc& acc, const Unit& u, int wr, int wc, int fr, int fq) const {
;     ...
;             for (int ai = 0; ai < 2; ++ai) {
;                 const int gi = u.pm * 4 + ai * 2 + wr;
;                 f32x4 pa = (f32x4){0.f, 0.f, 0.f, 0.f}, pg = pa;
; #pragma unroll
;                 for (int m = 0; m < 4; ++m) {
;                     const f32x4 ca = acc[ai][0][m][n], cg = acc[ai][1][m][n];
;                     f32x4 o;
; #pragma unroll
;                     for (int e = 0; e < 4; ++e) {
;                         const float ta1 = (fr == 15) ? pa[e] : ca[e], ta2 = (fr >= 14) ? pa[e] : ca[e], tg1 = (fr == 15) ? pg[e] : cg[e], tg2 = (fr >= 14) ? pg[e] : cg[e];
;                         const float a1 = dpp_ror<0x121>(ta1), a2 = dpp_ror<0x122>(ta2), g1 = dpp_ror<0x121>(tg1), g2 = dpp_ror<0x122>(tg2);
;                         const float va = ba[e] + wa0[e] * a2 + wa1[e] * a1 + wa2[e] * ca[e];
;                         const float vg = bg[e] + wg0[e] * g2 + wg1[e] * g1 + wg2[e] * cg[e];
;                         o[e] = vg * sigmoidf_(vg) * va;
;                     }
;                     const int row = u.pm * BM + ai * HALF + wr * 64 + m * 16 + fr;
;                     if (!(m == 0 && fr < 2)) { v2u w; w.x = pk2a(o[0], o[1]); w.y = pk2a(o[2], o[3]); *(v2u*)(ACT + (size_t)row * FF + j4) = w; }
.LBB0_912:
	s_or_b64 exec, exec, s[52:53]
	v_cndmask_b32_e64 v99, v94, 0, s[2:3]
	v_mov_b32_e32 v98, 0
	v_mov_b32_e32 v100, 0
	v_mov_b32_e32 v122, 0
	v_mov_b32_dpp v98, v99 row_ror:1 row_mask:0xf bank_mask:0xf
	v_cndmask_b32_e64 v99, v94, 0, s[4:5]
	v_mov_b32_e32 v124, 0
	v_mov_b32_e32 v102, 0
	v_mov_b32_dpp v100, v99 row_ror:2 row_mask:0xf bank_mask:0xf
	v_cndmask_b32_e64 v99, v90, 0, s[2:3]
	v_mov_b32_e32 v104, 0
	v_mov_b32_e32 v132, 0
	v_mov_b32_dpp v122, v99 row_ror:1 row_mask:0xf bank_mask:0xf
	v_cndmask_b32_e64 v99, v90, 0, s[4:5]
	v_mov_b32_e32 v136, 0
	v_cndmask_b32_e64 v101, v96, 0, s[2:3]
	v_mov_b32_dpp v124, v99 row_ror:2 row_mask:0xf bank_mask:0xf
	v_cndmask_b32_e64 v99, v95, 0, s[2:3]
	v_cndmask_b32_e64 v103, v96, 0, s[4:5]
	v_mov_b32_e32 v123, 0
	v_mov_b32_dpp v102, v99 row_ror:1 row_mask:0xf bank_mask:0xf
	v_cndmask_b32_e64 v99, v95, 0, s[4:5]
	v_mov_b32_e32 v125, 0
	v_cndmask_b32_e64 v105, v97, 0, s[2:3]
	v_mov_b32_dpp v104, v99 row_ror:2 row_mask:0xf bank_mask:0xf
	v_cndmask_b32_e64 v99, v91, 0, s[2:3]
	v_cndmask_b32_e64 v133, v97, 0, s[4:5]
	v_cndmask_b32_e64 v137, v93, 0, s[2:3]
	v_mov_b32_dpp v132, v99 row_ror:1 row_mask:0xf bank_mask:0xf
	v_cndmask_b32_e64 v99, v91, 0, s[4:5]
	v_cndmask_b32_e64 v140, v93, 0, s[4:5]
	v_add_u32_e32 v146, 0x80, v220
	v_mov_b32_dpp v136, v99 row_ror:2 row_mask:0xf bank_mask:0xf
	v_mov_b32_e32 v99, 0
	s_nop 1
	v_mov_b32_dpp v99, v101 row_ror:1 row_mask:0xf bank_mask:0xf
	v_mov_b32_e32 v101, 0
	s_nop 1
	v_mov_b32_dpp v101, v103 row_ror:2 row_mask:0xf bank_mask:0xf
	v_cndmask_b32_e64 v103, v92, 0, s[2:3]
	s_nop 1
	v_mov_b32_dpp v123, v103 row_ror:1 row_mask:0xf bank_mask:0xf
	v_cndmask_b32_e64 v103, v92, 0, s[4:5]
	s_nop 1
	v_mov_b32_dpp v125, v103 row_ror:2 row_mask:0xf bank_mask:0xf
	v_mov_b32_e32 v103, 0
	s_nop 1
	v_mov_b32_dpp v103, v105 row_ror:1 row_mask:0xf bank_mask:0xf
	v_mov_b32_e32 v105, 0
	s_nop 1
	v_mov_b32_dpp v105, v133 row_ror:2 row_mask:0xf bank_mask:0xf
	v_mov_b32_e32 v133, 0
	s_nop 1
	v_mov_b32_dpp v133, v137 row_ror:1 row_mask:0xf bank_mask:0xf
	v_mov_b32_e32 v137, 0
	s_nop 1
	v_mov_b32_dpp v137, v140 row_ror:2 row_mask:0xf bank_mask:0xf
	s_and_saveexec_b64 s[52:53], s[6:7]
	s_xor_b64 s[52:53], exec, s[52:53]
	s_cbranch_execz .LBB0_914
	v_pk_mul_f32 v[152:153], v[92:93], v[144:145]
	v_pk_mul_f32 v[154:155], v[90:91], v[142:143]
	v_pk_fma_f32 v[136:137], v[196:197], v[136:137], v[200:201]
	v_mov_b32_e32 v156, v155
	v_mov_b32_e32 v157, v153
	v_pk_fma_f32 v[132:133], v[192:193], v[132:133], v[136:137]
	v_pk_fma_f32 v[124:125], v[134:135], v[124:125], v[138:139]
	v_pk_add_f32 v[132:133], v[156:157], v[132:133]
	v_mov_b32_e32 v155, v152
	v_mul_f32_e32 v136, 0xbfb8aa3b, v133
	v_exp_f32_e32 v136, v136
	v_pk_fma_f32 v[122:123], v[130:131], v[122:123], v[124:125]
	v_pk_fma_f32 v[104:105], v[194:195], v[104:105], v[198:199]
	v_pk_add_f32 v[122:123], v[154:155], v[122:123]
	v_add_f32_e32 v125, 1.0, v136
	v_mul_f32_e32 v124, 0xbfb8aa3b, v123
	v_mul_f32_e32 v136, 0xbfb8aa3b, v132
	v_exp_f32_e32 v124, v124
	v_exp_f32_e32 v136, v136
	v_pk_fma_f32 v[102:103], v[190:191], v[102:103], v[104:105]
	v_rcp_f32_e32 v125, v125
	v_add_f32_e32 v124, 1.0, v124
	v_add_f32_e32 v104, 1.0, v136
	v_rcp_f32_e32 v137, v124
	v_rcp_f32_e32 v124, v104
	v_mul_f32_e32 v104, 0xbfb8aa3b, v122
	v_exp_f32_e32 v136, v104
	v_pk_mul_f32 v[140:141], v[96:97], v[128:129]
	v_pk_mul_f32 v[148:149], v[94:95], v[126:127]
	v_mov_b32_e32 v151, v141
	v_mov_b32_e32 v150, v149
	v_pk_add_f32 v[102:103], v[150:151], v[102:103]
	v_pk_mul_f32 v[104:105], v[132:133], v[124:125]
	v_pk_fma_f32 v[100:101], v[110:111], v[100:101], v[118:119]
	v_pk_mul_f32 v[102:103], v[102:103], v[104:105]
	v_add_f32_e32 v104, 1.0, v136
	v_rcp_f32_e32 v136, v104
	v_mov_b32_e32 v149, v140
	v_pk_fma_f32 v[98:99], v[114:115], v[98:99], v[100:101]
	v_pk_mul_f32 v[100:101], v[122:123], v[136:137]
	v_pk_add_f32 v[98:99], v[148:149], v[98:99]
	s_nop 0
	v_pk_mul_f32 v[98:99], v[98:99], v[100:101]
	v_add_u32_e32 v100, 0x10000, v103
	v_add_u32_e32 v98, 0x10000, v98
	v_add_u32_e32 v99, 0x10000, v99
	v_add_u32_e32 v101, 0x10000, v102
	v_and_b32_e32 v100, 0xfffe0000, v100
	v_and_b32_e32 v101, 0xfffe0000, v101
	v_and_b32_sdwa v99, v99, s72 dst_sel:DWORD dst_unused:UNUSED_PAD src0_sel:WORD_1 src1_sel:DWORD
	v_and_b32_sdwa v98, v98, s72 dst_sel:DWORD dst_unused:UNUSED_PAD src0_sel:WORD_1 src1_sel:DWORD
	v_or_b32_e32 v99, v100, v99
	v_or_b32_e32 v98, v101, v98
	v_mov_b64_e32 v[100:101], s[20:21]
	v_mad_i64_i32 v[100:101], s[54:55], v146, s70, v[100:101]
	v_lshl_add_u64 v[100:101], v[184:185], 1, v[100:101]
	v_mov_b32_e32 v246, v98
	v_mov_b32_e32 v247, v99

; __device__ __forceinline__ float sigmoidf_(float x) { return __builtin_amdgcn_rcpf(1.0f + __builtin_amdgcn_exp2f(-x * LOG2E)); }
; template <int CTRL> __device__ __forceinline__ float dpp_ror(float v) { return __builtin_bit_cast(float, __builtin_amdgcn_update_dpp(0, __builtin_bit_cast(int, v), CTRL, 0xf, 0xf, false)); }
;     __device__ __forceinline__ void operator()(const Acc& acc, const Unit& u, int wr, int wc, int fr, int fq) const {
;     ...
;                 for (int m = 0; m < 4; ++m) {
;                     const f32x4 ca = acc[ai][0][m][n], cg = acc[ai][1][m][n];
;                     f32x4 o;
; #pragma unroll
;                     for (int e = 0; e < 4; ++e) {
;                         const float ta1 = (fr == 15) ? pa[e] : ca[e], ta2 = (fr >= 14) ? pa[e] : ca[e], tg1 = (fr == 15) ? pg[e] : cg[e], tg2 = (fr >= 14) ? pg[e] : cg[e];
;                         const float a1 = dpp_ror<0x121>(ta1), a2 = dpp_ror<0x122>(ta2), g1 = dpp_ror<0x121>(tg1), g2 = dpp_ror<0x122>(tg2);
;                         const float va = ba[e] + wa0[e] * a2 + wa1[e] * a1 + wa2[e] * ca[e];
;                         const float vg = bg[e] + wg0[e] * g2 + wg1[e] * g1 + wg2[e] * cg[e];
;                         o[e] = vg * sigmoidf_(vg) * va;
;                     }
;                     const int row = u.pm * BM + ai * HALF + wr * 64 + m * 16 + fr;
;                     if (!(m == 0 && fr < 2)) { v2u w; w.x = pk2a(o[0], o[1]); w.y = pk2a(o[2], o[3]); *(v2u*)(ACT + (size_t)row * FF + j4) = w; }
.LBB0_916:
	s_or_b64 exec, exec, s[52:53]
	v_cndmask_b32_e64 v98, v86, v94, s[2:3]
	v_cndmask_b32_e64 v100, v82, v90, s[2:3]
	v_cndmask_b32_e64 v101, v82, v90, s[4:5]
	v_mov_b32_e32 v90, 0
	v_cndmask_b32_e64 v99, v86, v94, s[4:5]
	v_mov_b32_e32 v94, 0
	v_mov_b32_dpp v90, v98 row_ror:1 row_mask:0xf bank_mask:0xf
	v_mov_b32_e32 v98, 0
	v_mov_b32_dpp v94, v99 row_ror:2 row_mask:0xf bank_mask:0xf
	v_cndmask_b32_e64 v99, v87, v95, s[2:3]
	v_mov_b32_dpp v98, v100 row_ror:1 row_mask:0xf bank_mask:0xf
	v_mov_b32_e32 v100, 0
	v_cndmask_b32_e64 v95, v87, v95, s[4:5]
	v_mov_b32_e32 v102, 0
	v_mov_b32_dpp v100, v101 row_ror:2 row_mask:0xf bank_mask:0xf
	v_cndmask_b32_e64 v101, v83, v91, s[2:3]
	v_cndmask_b32_e64 v91, v83, v91, s[4:5]
	v_mov_b32_e32 v104, 0
	v_mov_b32_e32 v122, 0
	v_mov_b32_e32 v124, 0
	v_mov_b32_dpp v102, v99 row_ror:1 row_mask:0xf bank_mask:0xf
	v_mov_b32_dpp v104, v95 row_ror:2 row_mask:0xf bank_mask:0xf
	v_mov_b32_dpp v122, v101 row_ror:1 row_mask:0xf bank_mask:0xf
	v_mov_b32_dpp v124, v91 row_ror:2 row_mask:0xf bank_mask:0xf
	v_cndmask_b32_e64 v95, v88, v96, s[2:3]
	v_cndmask_b32_e64 v101, v84, v92, s[2:3]
	v_mov_b32_e32 v91, 0
	v_mov_b32_e32 v99, 0
	v_cndmask_b32_e64 v96, v88, v96, s[4:5]
	v_cndmask_b32_e64 v92, v84, v92, s[4:5]
	v_mov_b32_dpp v91, v95 row_ror:1 row_mask:0xf bank_mask:0xf
	v_mov_b32_e32 v95, 0
	v_mov_b32_dpp v99, v101 row_ror:1 row_mask:0xf bank_mask:0xf
	v_mov_b32_e32 v101, 0
	v_mov_b32_dpp v95, v96 row_ror:2 row_mask:0xf bank_mask:0xf
	v_cndmask_b32_e64 v96, v89, v97, s[4:5]
	v_mov_b32_dpp v101, v92 row_ror:2 row_mask:0xf bank_mask:0xf
	v_cndmask_b32_e64 v92, v89, v97, s[2:3]
	v_cndmask_b32_e64 v97, v85, v93, s[2:3]
	v_cndmask_b32_e64 v93, v85, v93, s[4:5]
	v_mov_b32_e32 v125, 0
	v_mov_b32_e32 v103, 0
	v_mov_b32_e32 v105, 0
	v_mov_b32_e32 v123, 0
	v_mov_b32_dpp v125, v93 row_ror:2 row_mask:0xf bank_mask:0xf
	v_mov_b32_dpp v103, v92 row_ror:1 row_mask:0xf bank_mask:0xf
	v_mov_b32_dpp v105, v96 row_ror:2 row_mask:0xf bank_mask:0xf
	v_mov_b32_dpp v123, v97 row_ror:1 row_mask:0xf bank_mask:0xf
	v_pk_mul_f32 v[92:93], v[84:85], v[144:145]
	v_pk_mul_f32 v[96:97], v[82:83], v[142:143]
	v_pk_fma_f32 v[124:125], v[196:197], v[124:125], v[200:201]
	v_mov_b32_e32 v132, v97
	v_mov_b32_e32 v133, v93
	v_pk_fma_f32 v[122:123], v[192:193], v[122:123], v[124:125]
	v_mov_b32_e32 v97, v92
	v_pk_add_f32 v[122:123], v[132:133], v[122:123]
	v_pk_fma_f32 v[104:105], v[194:195], v[104:105], v[198:199]
	v_mul_f32_e32 v93, 0xbfb8aa3b, v123
	v_exp_f32_e32 v124, v93
	v_pk_fma_f32 v[92:93], v[134:135], v[100:101], v[138:139]
	v_pk_mul_f32 v[100:101], v[88:89], v[128:129]
	v_pk_fma_f32 v[92:93], v[130:131], v[98:99], v[92:93]
	v_pk_fma_f32 v[94:95], v[110:111], v[94:95], v[118:119]
	v_pk_add_f32 v[92:93], v[96:97], v[92:93]
	v_add_f32_e32 v97, 1.0, v124
	v_mul_f32_e32 v96, 0xbfb8aa3b, v93
	v_exp_f32_e32 v96, v96
	v_mul_f32_e32 v98, 0xbfb8aa3b, v92
	v_exp_f32_e32 v98, v98
	v_rcp_f32_e32 v97, v97
	v_add_f32_e32 v96, 1.0, v96
	v_rcp_f32_e32 v99, v96
	v_mul_f32_e32 v96, 0xbfb8aa3b, v122
	v_exp_f32_e32 v96, v96
	v_add_f32_e32 v98, 1.0, v98
	v_rcp_f32_e32 v98, v98
	v_pk_mul_f32 v[124:125], v[86:87], v[126:127]
	v_add_f32_e32 v96, 1.0, v96
	v_rcp_f32_e32 v96, v96
	v_mov_b32_e32 v132, v125
	v_mov_b32_e32 v133, v101
	v_pk_fma_f32 v[102:103], v[190:191], v[102:103], v[104:105]
	v_mov_b32_e32 v125, v100
	v_pk_fma_f32 v[90:91], v[114:115], v[90:91], v[94:95]
	v_pk_add_f32 v[102:103], v[132:133], v[102:103]
	v_pk_mul_f32 v[96:97], v[122:123], v[96:97]
	v_pk_add_f32 v[90:91], v[124:125], v[90:91]
	v_pk_mul_f32 v[92:93], v[92:93], v[98:99]
	v_pk_mul_f32 v[96:97], v[102:103], v[96:97]
	v_pk_mul_f32 v[90:91], v[90:91], v[92:93]
	v_add_u32_e32 v92, 0x10000, v97
	v_add_u32_e32 v90, 0x10000, v90
	v_add_u32_e32 v91, 0x10000, v91
	v_add_u32_e32 v93, 0x10000, v96
	v_and_b32_e32 v92, 0xfffe0000, v92
	v_and_b32_e32 v94, 0xfffe0000, v93
	v_and_b32_sdwa v91, v91, s72 dst_sel:DWORD dst_unused:UNUSED_PAD src0_sel:WORD_1 src1_sel:DWORD
	v_and_b32_sdwa v90, v90, s72 dst_sel:DWORD dst_unused:UNUSED_PAD src0_sel:WORD_1 src1_sel:DWORD
	v_add_u32_e32 v136, 0x90, v220
	v_or_b32_e32 v93, v92, v91
	v_or_b32_e32 v92, v94, v90
	v_mov_b64_e32 v[90:91], s[20:21]
	v_mad_i64_i32 v[94:95], s[52:53], v136, s70, v[90:91]
	v_lshl_add_u64 v[100:101], v[94:95], 0, v[120:121]
	v_mov_b32_e32 v248, v92
	v_mov_b32_e32 v249, v93
	v_cndmask_b32_e64 v92, v78, v86, s[2:3]
	v_cndmask_b32_e64 v94, v74, v82, s[2:3]
	v_cndmask_b32_e64 v95, v74, v82, s[4:5]
	v_mov_b32_e32 v82, 0
	v_cndmask_b32_e64 v93, v78, v86, s[4:5]
	v_mov_b32_e32 v86, 0
	v_mov_b32_dpp v82, v92 row_ror:1 row_mask:0xf bank_mask:0xf
	v_mov_b32_e32 v92, 0
	v_mov_b32_dpp v86, v93 row_ror:2 row_mask:0xf bank_mask:0xf
	v_cndmask_b32_e64 v93, v79, v87, s[2:3]
	v_mov_b32_dpp v92, v94 row_ror:1 row_mask:0xf bank_mask:0xf
	v_mov_b32_e32 v94, 0
	v_cndmask_b32_e64 v87, v79, v87, s[4:5]
	v_mov_b32_e32 v96, 0
	v_mov_b32_dpp v94, v95 row_ror:2 row_mask:0xf bank_mask:0xf
	v_cndmask_b32_e64 v95, v75, v83, s[2:3]
	v_cndmask_b32_e64 v83, v75, v83, s[4:5]
	v_mov_b32_e32 v98, 0
	v_mov_b32_e32 v102, 0
	v_mov_b32_e32 v104, 0
	v_mov_b32_dpp v96, v93 row_ror:1 row_mask:0xf bank_mask:0xf
	v_mov_b32_dpp v98, v87 row_ror:2 row_mask:0xf bank_mask:0xf
	v_mov_b32_dpp v102, v95 row_ror:1 row_mask:0xf bank_mask:0xf
	v_mov_b32_dpp v104, v83 row_ror:2 row_mask:0xf bank_mask:0xf
	v_cndmask_b32_e64 v87, v80, v88, s[2:3]
	v_cndmask_b32_e64 v95, v76, v84, s[2:3]
	v_mov_b32_e32 v83, 0
	v_mov_b32_e32 v93, 0
	v_cndmask_b32_e64 v88, v80, v88, s[4:5]
	v_cndmask_b32_e64 v84, v76, v84, s[4:5]
	v_mov_b32_dpp v83, v87 row_ror:1 row_mask:0xf bank_mask:0xf
	v_mov_b32_e32 v87, 0
; __device__ __forceinline__ float sigmoidf_(float x) { return __builtin_amdgcn_rcpf(1.0f + __builtin_amdgcn_exp2f(-x * LOG2E)); }
; template <int CTRL> __device__ __forceinline__ float dpp_ror(float v) { return __builtin_bit_cast(float, __builtin_amdgcn_update_dpp(0, __builtin_bit_cast(int, v), CTRL, 0xf, 0xf, false)); }
;     __device__ __forceinline__ void operator()(const Acc& acc, const Unit& u, int wr, int wc, int fr, int fq) const {
;     ...
;                 for (int m = 0; m < 4; ++m) {
;                     const f32x4 ca = acc[ai][0][m][n], cg = acc[ai][1][m][n];
;                     f32x4 o;
; #pragma unroll
;                     for (int e = 0; e < 4; ++e) {
;                         const float ta1 = (fr == 15) ? pa[e] : ca[e], ta2 = (fr >= 14) ? pa[e] : ca[e], tg1 = (fr == 15) ? pg[e] : cg[e], tg2 = (fr >= 14) ? pg[e] : cg[e];
;                         const float a1 = dpp_ror<0x121>(ta1), a2 = dpp_ror<0x122>(ta2), g1 = dpp_ror<0x121>(tg1), g2 = dpp_ror<0x122>(tg2);
;                         const float va = ba[e] + wa0[e] * a2 + wa1[e] * a1 + wa2[e] * ca[e];
;                         const float vg = bg[e] + wg0[e] * g2 + wg1[e] * g1 + wg2[e] * cg[e];
;                         o[e] = vg * sigmoidf_(vg) * va;
;                     }
;                     const int row = u.pm * BM + ai * HALF + wr * 64 + m * 16 + fr;
;                     if (!(m == 0 && fr < 2)) { v2u w; w.x = pk2a(o[0], o[1]); w.y = pk2a(o[2], o[3]); *(v2u*)(ACT + (size_t)row * FF + j4) = w; }
	v_mov_b32_dpp v93, v95 row_ror:1 row_mask:0xf bank_mask:0xf
	v_mov_b32_e32 v95, 0
	v_mov_b32_dpp v87, v88 row_ror:2 row_mask:0xf bank_mask:0xf
	v_cndmask_b32_e64 v88, v81, v89, s[4:5]
	v_mov_b32_dpp v95, v84 row_ror:2 row_mask:0xf bank_mask:0xf
	v_cndmask_b32_e64 v84, v81, v89, s[2:3]
	v_cndmask_b32_e64 v89, v77, v85, s[2:3]
	v_cndmask_b32_e64 v85, v77, v85, s[4:5]
	v_mov_b32_e32 v105, 0
	v_mov_b32_e32 v97, 0
	v_mov_b32_e32 v99, 0
	v_mov_b32_e32 v103, 0
	v_mov_b32_dpp v105, v85 row_ror:2 row_mask:0xf bank_mask:0xf
	v_mov_b32_dpp v97, v84 row_ror:1 row_mask:0xf bank_mask:0xf
	v_mov_b32_dpp v99, v88 row_ror:2 row_mask:0xf bank_mask:0xf
	v_mov_b32_dpp v103, v89 row_ror:1 row_mask:0xf bank_mask:0xf
	v_pk_mul_f32 v[84:85], v[76:77], v[144:145]
	v_pk_mul_f32 v[88:89], v[74:75], v[142:143]
	v_pk_fma_f32 v[104:105], v[196:197], v[104:105], v[200:201]
	v_mov_b32_e32 v122, v89
	v_mov_b32_e32 v123, v85
	v_pk_fma_f32 v[102:103], v[192:193], v[102:103], v[104:105]
	v_mov_b32_e32 v89, v84
	v_pk_add_f32 v[102:103], v[122:123], v[102:103]
	v_pk_fma_f32 v[98:99], v[194:195], v[98:99], v[198:199]
	v_mul_f32_e32 v85, 0xbfb8aa3b, v103
	v_exp_f32_e32 v104, v85
	v_pk_fma_f32 v[84:85], v[134:135], v[94:95], v[138:139]
	v_pk_mul_f32 v[94:95], v[80:81], v[128:129]
	v_pk_fma_f32 v[84:85], v[130:131], v[92:93], v[84:85]
	v_pk_fma_f32 v[86:87], v[110:111], v[86:87], v[118:119]
	v_pk_add_f32 v[84:85], v[88:89], v[84:85]
	v_add_f32_e32 v89, 1.0, v104
	v_mul_f32_e32 v88, 0xbfb8aa3b, v85
	v_exp_f32_e32 v88, v88
	v_mul_f32_e32 v92, 0xbfb8aa3b, v84
	v_exp_f32_e32 v92, v92
	v_rcp_f32_e32 v89, v89
	v_add_f32_e32 v88, 1.0, v88
	v_rcp_f32_e32 v93, v88
	v_mul_f32_e32 v88, 0xbfb8aa3b, v102
	v_exp_f32_e32 v88, v88
	v_add_f32_e32 v92, 1.0, v92
	v_rcp_f32_e32 v92, v92
	v_pk_mul_f32 v[104:105], v[78:79], v[126:127]
	v_add_f32_e32 v88, 1.0, v88
	v_rcp_f32_e32 v88, v88
	v_mov_b32_e32 v122, v105
	v_mov_b32_e32 v123, v95
	v_pk_fma_f32 v[96:97], v[190:191], v[96:97], v[98:99]
	v_mov_b32_e32 v105, v94
	v_pk_fma_f32 v[82:83], v[114:115], v[82:83], v[86:87]
	v_pk_add_f32 v[96:97], v[122:123], v[96:97]
	v_pk_mul_f32 v[88:89], v[102:103], v[88:89]
	v_pk_add_f32 v[82:83], v[104:105], v[82:83]
	v_pk_mul_f32 v[84:85], v[84:85], v[92:93]
	v_pk_mul_f32 v[88:89], v[96:97], v[88:89]
	v_pk_mul_f32 v[82:83], v[82:83], v[84:85]
	v_add_u32_e32 v84, 0x10000, v89
	v_add_u32_e32 v82, 0x10000, v82
	v_add_u32_e32 v83, 0x10000, v83
	v_add_u32_e32 v85, 0x10000, v88
	v_add_u32_e32 v124, 0xa0, v220
	v_and_b32_e32 v84, 0xfffe0000, v84
	v_and_b32_e32 v85, 0xfffe0000, v85
	v_and_b32_sdwa v83, v83, s72 dst_sel:DWORD dst_unused:UNUSED_PAD src0_sel:WORD_1 src1_sel:DWORD
	v_and_b32_sdwa v82, v82, s72 dst_sel:DWORD dst_unused:UNUSED_PAD src0_sel:WORD_1 src1_sel:DWORD
	v_or_b32_e32 v83, v84, v83
	v_or_b32_e32 v82, v85, v82
	v_mad_i64_i32 v[84:85], s[52:53], v124, s70, v[90:91]
	v_lshl_add_u64 v[102:103], v[84:85], 0, v[120:121]
	v_mov_b32_e32 v250, v82
	v_mov_b32_e32 v251, v83
	v_cndmask_b32_e64 v82, v70, v78, s[2:3]
	v_cndmask_b32_e64 v84, v66, v74, s[2:3]
	v_cndmask_b32_e64 v85, v66, v74, s[4:5]
	v_mov_b32_e32 v74, 0
	v_cndmask_b32_e64 v83, v70, v78, s[4:5]
	v_mov_b32_e32 v78, 0
	v_mov_b32_dpp v74, v82 row_ror:1 row_mask:0xf bank_mask:0xf
	v_mov_b32_e32 v82, 0
	v_mov_b32_dpp v78, v83 row_ror:2 row_mask:0xf bank_mask:0xf
	v_cndmask_b32_e64 v83, v71, v79, s[2:3]
	v_mov_b32_dpp v82, v84 row_ror:1 row_mask:0xf bank_mask:0xf
	v_mov_b32_e32 v84, 0
	v_cndmask_b32_e64 v79, v71, v79, s[4:5]
	v_mov_b32_e32 v86, 0
	v_mov_b32_dpp v84, v85 row_ror:2 row_mask:0xf bank_mask:0xf
	v_cndmask_b32_e64 v85, v67, v75, s[2:3]
	v_cndmask_b32_e64 v75, v67, v75, s[4:5]
	v_mov_b32_e32 v88, 0
	v_mov_b32_e32 v92, 0
	v_mov_b32_e32 v94, 0
	v_mov_b32_dpp v86, v83 row_ror:1 row_mask:0xf bank_mask:0xf
	v_mov_b32_dpp v88, v79 row_ror:2 row_mask:0xf bank_mask:0xf
	v_mov_b32_dpp v92, v85 row_ror:1 row_mask:0xf bank_mask:0xf
	v_mov_b32_dpp v94, v75 row_ror:2 row_mask:0xf bank_mask:0xf
	v_cndmask_b32_e64 v79, v72, v80, s[2:3]
	v_cndmask_b32_e64 v85, v68, v76, s[2:3]
	v_mov_b32_e32 v75, 0
	v_mov_b32_e32 v83, 0
	v_cndmask_b32_e64 v80, v72, v80, s[4:5]
	v_cndmask_b32_e64 v76, v68, v76, s[4:5]
	v_mov_b32_dpp v75, v79 row_ror:1 row_mask:0xf bank_mask:0xf
	v_mov_b32_e32 v79, 0
	v_mov_b32_dpp v83, v85 row_ror:1 row_mask:0xf bank_mask:0xf
	v_mov_b32_e32 v85, 0
	v_mov_b32_dpp v79, v80 row_ror:2 row_mask:0xf bank_mask:0xf
	v_cndmask_b32_e64 v80, v73, v81, s[4:5]
	v_mov_b32_dpp v85, v76 row_ror:2 row_mask:0xf bank_mask:0xf
	v_cndmask_b32_e64 v76, v73, v81, s[2:3]
	v_cndmask_b32_e64 v81, v69, v77, s[2:3]
	v_cndmask_b32_e64 v77, v69, v77, s[4:5]
	v_mov_b32_e32 v95, 0
	v_mov_b32_e32 v87, 0
	v_mov_b32_e32 v89, 0
	v_mov_b32_e32 v93, 0
	v_mov_b32_dpp v95, v77 row_ror:2 row_mask:0xf bank_mask:0xf
	v_mov_b32_dpp v87, v76 row_ror:1 row_mask:0xf bank_mask:0xf
	v_mov_b32_dpp v89, v80 row_ror:2 row_mask:0xf bank_mask:0xf
	v_mov_b32_dpp v93, v81 row_ror:1 row_mask:0xf bank_mask:0xf
	v_pk_mul_f32 v[76:77], v[68:69], v[144:145]
	v_pk_mul_f32 v[80:81], v[66:67], v[142:143]
	v_pk_fma_f32 v[94:95], v[196:197], v[94:95], v[200:201]
	v_mov_b32_e32 v96, v81
	v_mov_b32_e32 v97, v77
	v_pk_fma_f32 v[92:93], v[192:193], v[92:93], v[94:95]
	v_mov_b32_e32 v81, v76
	v_pk_add_f32 v[92:93], v[96:97], v[92:93]
	v_pk_fma_f32 v[88:89], v[194:195], v[88:89], v[198:199]
	v_mul_f32_e32 v77, 0xbfb8aa3b, v93
	v_exp_f32_e32 v94, v77
	v_pk_fma_f32 v[76:77], v[134:135], v[84:85], v[138:139]
	v_pk_mul_f32 v[84:85], v[72:73], v[128:129]
	v_pk_fma_f32 v[76:77], v[130:131], v[82:83], v[76:77]
	v_pk_fma_f32 v[78:79], v[110:111], v[78:79], v[118:119]
	v_pk_add_f32 v[76:77], v[80:81], v[76:77]
	v_add_f32_e32 v81, 1.0, v94
; __device__ __forceinline__ unsigned pk2(float lo, float hi) { unsigned r; asm("v_cvt_pk_bf16_f32 %0, %1, %2" : "=v"(r) : "v"(lo), "v"(hi)); return r; }
; __device__ __forceinline__ float sigmoidf_(float x) { return __builtin_amdgcn_rcpf(1.0f + __builtin_amdgcn_exp2f(-x * LOG2E)); }
; template <int CTRL> __device__ __forceinline__ float dpp_ror(float v) { return __builtin_bit_cast(float, __builtin_amdgcn_update_dpp(0, __builtin_bit_cast(int, v), CTRL, 0xf, 0xf, false)); }
;     __device__ __forceinline__ void operator()(const Acc& acc, const Unit& u, int wr, int wc, int fr, int fq) const {
;     ...
;                 for (int m = 0; m < 4; ++m) {
;                     const f32x4 ca = acc[ai][0][m][n], cg = acc[ai][1][m][n];
;                     f32x4 o;
; #pragma unroll
;                     for (int e = 0; e < 4; ++e) {
;                         const float ta1 = (fr == 15) ? pa[e] : ca[e], ta2 = (fr >= 14) ? pa[e] : ca[e], tg1 = (fr == 15) ? pg[e] : cg[e], tg2 = (fr >= 14) ? pg[e] : cg[e];
;                         const float a1 = dpp_ror<0x121>(ta1), a2 = dpp_ror<0x122>(ta2), g1 = dpp_ror<0x121>(tg1), g2 = dpp_ror<0x122>(tg2);
;                         const float va = ba[e] + wa0[e] * a2 + wa1[e] * a1 + wa2[e] * ca[e];
;                         const float vg = bg[e] + wg0[e] * g2 + wg1[e] * g1 + wg2[e] * cg[e];
;                         o[e] = vg * sigmoidf_(vg) * va;
;                     }
;                     const int row = u.pm * BM + ai * HALF + wr * 64 + m * 16 + fr;
;                     if (!(m == 0 && fr < 2)) { v2u w; w.x = pk2a(o[0], o[1]); w.y = pk2a(o[2], o[3]); *(v2u*)(ACT + (size_t)row * FF + j4) = w; }
;                     if ((m == 0 && fr < 2) || (m == 3 && fr >= 14)) {
;                         const int slot = (m == 0) ? fr : fr - 12;
;                         bf16* rp = RAW + ((size_t)gi * 4 + slot) * NUP + rawcol;
;                         v2u w; w.x = pk2(ca[0], ca[1]); w.y = pk2(ca[2], ca[3]); *(v2u*)rp = w;
;                         w.x = pk2(cg[0], cg[1]); w.y = pk2(cg[2], cg[3]); *(v2u*)(rp + HALF) = w;
;                     }
	v_mul_f32_e32 v80, 0xbfb8aa3b, v77
	v_exp_f32_e32 v80, v80
	v_mul_f32_e32 v82, 0xbfb8aa3b, v76
	v_exp_f32_e32 v82, v82
	v_rcp_f32_e32 v81, v81
	v_add_f32_e32 v80, 1.0, v80
	v_rcp_f32_e32 v83, v80
	v_mul_f32_e32 v80, 0xbfb8aa3b, v92
	v_exp_f32_e32 v80, v80
	v_add_f32_e32 v82, 1.0, v82
	v_rcp_f32_e32 v82, v82
	v_pk_mul_f32 v[94:95], v[70:71], v[126:127]
	v_add_f32_e32 v80, 1.0, v80
	v_rcp_f32_e32 v80, v80
	v_mov_b32_e32 v96, v95
	v_mov_b32_e32 v97, v85
	v_pk_fma_f32 v[86:87], v[190:191], v[86:87], v[88:89]
	v_mov_b32_e32 v95, v84
	v_pk_fma_f32 v[74:75], v[114:115], v[74:75], v[78:79]
	v_pk_add_f32 v[86:87], v[96:97], v[86:87]
	v_pk_mul_f32 v[80:81], v[92:93], v[80:81]
	v_pk_add_f32 v[74:75], v[94:95], v[74:75]
	v_pk_mul_f32 v[76:77], v[76:77], v[82:83]
	v_pk_mul_f32 v[80:81], v[86:87], v[80:81]
	v_pk_mul_f32 v[74:75], v[74:75], v[76:77]
	v_add_u32_e32 v76, 0x10000, v81
	v_add_u32_e32 v74, 0x10000, v74
	v_add_u32_e32 v75, 0x10000, v75
	v_add_u32_e32 v77, 0x10000, v80
	v_add_u32_e32 v98, 0xb0, v220
	v_and_b32_e32 v76, 0xfffe0000, v76
	v_and_b32_e32 v77, 0xfffe0000, v77
	v_and_b32_sdwa v75, v75, s72 dst_sel:DWORD dst_unused:UNUSED_PAD src0_sel:WORD_1 src1_sel:DWORD
	v_and_b32_sdwa v74, v74, s72 dst_sel:DWORD dst_unused:UNUSED_PAD src0_sel:WORD_1 src1_sel:DWORD
	v_or_b32_e32 v75, v76, v75
	v_or_b32_e32 v74, v77, v74
	v_mad_i64_i32 v[76:77], s[52:53], v98, s70, v[90:91]
	v_lshl_add_u64 v[104:105], v[76:77], 0, v[120:121]
	v_lshl_add_u64 v[98:99], s[12:13], 0, v[172:173]
	v_mov_b32_e32 v254, v74
	v_mov_b32_e32 v255, v75
	s_and_saveexec_b64 s[52:53], s[4:5]
	s_cbranch_execz .LBB0_918
	v_mov_b64_e32 v[74:75], s[0:1]
	v_mad_u64_u32 v[74:75], s[54:55], v98, s71, v[74:75]
	v_mad_i32_i24 v75, v99, s71, v75
	v_lshl_add_u64 v[74:75], v[182:183], 1, v[74:75]
	v_cvt_pk_bf16_f32 v70, v70, v71
	v_cvt_pk_bf16_f32 v71, v72, v73
	global_store_dwordx2 v[74:75], v[70:71], off
	v_cvt_pk_bf16_f32 v66, v66, v67
	v_cvt_pk_bf16_f32 v67, v68, v69
	global_store_dwordx2 v[74:75], v[66:67], off offset:256
; __device__ __forceinline__ float sigmoidf_(float x) { return __builtin_amdgcn_rcpf(1.0f + __builtin_amdgcn_exp2f(-x * LOG2E)); }
; template <int CTRL> __device__ __forceinline__ float dpp_ror(float v) { return __builtin_bit_cast(float, __builtin_amdgcn_update_dpp(0, __builtin_bit_cast(int, v), CTRL, 0xf, 0xf, false)); }
;     __device__ __forceinline__ void operator()(const Acc& acc, const Unit& u, int wr, int wc, int fr, int fq) const {
;     ...
;         for (int n = 0; n < 2; ++n) {
;             const int j4 = u.pn * HALF + wc * 32 + 8 * fq + 4 * n;
;             const f32x4 wa0 = *(const f32x4*)(cw + j4), wa1 = *(const f32x4*)(cw + NUP + j4), wa2 = *(const f32x4*)(cw + 2 * NUP + j4), ba = *(const f32x4*)(cb + j4);
;             const f32x4 wg0 = *(const f32x4*)(cw + FF + j4), wg1 = *(const f32x4*)(cw + NUP + FF + j4), wg2 = *(const f32x4*)(cw + 2 * NUP + FF + j4), bg = *(const f32x4*)(cb + FF + j4);
;             const int rawcol = u.pn * BM + wc * 32 + 8 * fq + 4 * n;
; #pragma unroll
;             for (int ai = 0; ai < 2; ++ai) {
;                 const int gi = u.pm * 4 + ai * 2 + wr;
;                 f32x4 pa = (f32x4){0.f, 0.f, 0.f, 0.f}, pg = pa;
; #pragma unroll
;                 for (int m = 0; m < 4; ++m) {
;                     const f32x4 ca = acc[ai][0][m][n], cg = acc[ai][1][m][n];
;                     f32x4 o;
; #pragma unroll
;                     for (int e = 0; e < 4; ++e) {
;                         const float ta1 = (fr == 15) ? pa[e] : ca[e], ta2 = (fr >= 14) ? pa[e] : ca[e], tg1 = (fr == 15) ? pg[e] : cg[e], tg2 = (fr >= 14) ? pg[e] : cg[e];
;                         const float a1 = dpp_ror<0x121>(ta1), a2 = dpp_ror<0x122>(ta2), g1 = dpp_ror<0x121>(tg1), g2 = dpp_ror<0x122>(tg2);
;                         const float va = ba[e] + wa0[e] * a2 + wa1[e] * a1 + wa2[e] * ca[e];
;                         const float vg = bg[e] + wg0[e] * g2 + wg1[e] * g1 + wg2[e] * cg[e];
;                         o[e] = vg * sigmoidf_(vg) * va;
;                     }
;                     const int row = u.pm * BM + ai * HALF + wr * 64 + m * 16 + fr;
;                     if (!(m == 0 && fr < 2)) { v2u w; w.x = pk2a(o[0], o[1]); w.y = pk2a(o[2], o[3]); *(v2u*)(ACT + (size_t)row * FF + j4) = w; }
.LBB0_918:
	s_or_b64 exec, exec, s[52:53]
	v_or_b32_e32 v70, 4, v184
	v_ashrrev_i32_e32 v71, 31, v70
	v_lshlrev_b64 v[90:91], 2, v[70:71]
	v_lshl_add_u64 v[70:71], s[28:29], 0, v[90:91]
	v_lshl_add_u64 v[74:75], s[30:31], 0, v[90:91]
	global_load_dwordx4 v[66:69], v[186:187], off offset:16
	s_nop 0
	global_load_dwordx4 v[70:73], v[70:71], off
	s_nop 0
	global_load_dwordx4 v[78:81], v[74:75], off
	s_nop 0
	global_load_dwordx4 v[74:77], v[188:189], off offset:16
	v_lshl_add_u64 v[82:83], s[36:37], 0, v[90:91]
	v_lshl_add_u64 v[84:85], s[38:39], 0, v[90:91]
	v_lshl_add_u64 v[92:93], s[40:41], 0, v[90:91]
	v_lshl_add_u64 v[90:91], s[42:43], 0, v[90:91]
	global_load_dwordx4 v[86:89], v[82:83], off
	s_nop 0
	global_load_dwordx4 v[82:85], v[84:85], off
	v_cndmask_b32_e64 v110, v62, 0, s[2:3]
	global_load_dwordx4 v[94:97], v[92:93], off
	v_mov_b32_e32 v126, 0
	global_load_dwordx4 v[90:93], v[90:91], off
	v_mov_b32_e32 v128, 0
	v_mov_b32_dpp v126, v110 row_ror:1 row_mask:0xf bank_mask:0xf
	v_cndmask_b32_e64 v110, v62, 0, s[4:5]
	v_mov_b32_e32 v134, 0
	v_mov_b32_e32 v136, 0
	v_mov_b32_dpp v128, v110 row_ror:2 row_mask:0xf bank_mask:0xf
	v_cndmask_b32_e64 v110, v58, 0, s[2:3]
	v_mov_b32_e32 v130, 0
	v_mov_b32_e32 v132, 0
	v_mov_b32_dpp v134, v110 row_ror:1 row_mask:0xf bank_mask:0xf
	v_cndmask_b32_e64 v110, v58, 0, s[4:5]
	v_mov_b32_e32 v138, 0
	v_mov_b32_e32 v140, 0
	v_mov_b32_dpp v136, v110 row_ror:2 row_mask:0xf bank_mask:0xf
	v_cndmask_b32_e64 v110, v63, 0, s[2:3]
	v_mov_b32_e32 v127, 0
	v_mov_b32_e32 v129, 0
	v_mov_b32_dpp v130, v110 row_ror:1 row_mask:0xf bank_mask:0xf
	v_cndmask_b32_e64 v110, v63, 0, s[4:5]
	v_mov_b32_e32 v135, 0
	v_mov_b32_e32 v137, 0
	v_mov_b32_dpp v132, v110 row_ror:2 row_mask:0xf bank_mask:0xf
	v_cndmask_b32_e64 v110, v59, 0, s[2:3]
	v_mov_b32_e32 v131, 0
	v_mov_b32_e32 v133, 0
	v_mov_b32_dpp v138, v110 row_ror:1 row_mask:0xf bank_mask:0xf
	v_cndmask_b32_e64 v110, v59, 0, s[4:5]
	v_mov_b32_e32 v139, 0
	v_mov_b32_e32 v141, 0
	v_mov_b32_dpp v140, v110 row_ror:2 row_mask:0xf bank_mask:0xf
	v_cndmask_b32_e64 v110, v64, 0, s[2:3]
	s_nop 1
	v_mov_b32_dpp v127, v110 row_ror:1 row_mask:0xf bank_mask:0xf
	v_cndmask_b32_e64 v110, v64, 0, s[4:5]
	s_nop 1
	v_mov_b32_dpp v129, v110 row_ror:2 row_mask:0xf bank_mask:0xf
	v_cndmask_b32_e64 v110, v60, 0, s[2:3]
	s_nop 1
	v_mov_b32_dpp v135, v110 row_ror:1 row_mask:0xf bank_mask:0xf
	v_cndmask_b32_e64 v110, v60, 0, s[4:5]
	s_nop 1
	v_mov_b32_dpp v137, v110 row_ror:2 row_mask:0xf bank_mask:0xf
	v_cndmask_b32_e64 v110, v65, 0, s[2:3]
	s_nop 1
	v_mov_b32_dpp v131, v110 row_ror:1 row_mask:0xf bank_mask:0xf
	v_cndmask_b32_e64 v110, v65, 0, s[4:5]
	s_nop 1
	v_mov_b32_dpp v133, v110 row_ror:2 row_mask:0xf bank_mask:0xf
	v_cndmask_b32_e64 v110, v61, 0, s[2:3]
	s_nop 1
	v_mov_b32_dpp v139, v110 row_ror:1 row_mask:0xf bank_mask:0xf
	v_cndmask_b32_e64 v110, v61, 0, s[4:5]
	s_nop 1
	v_mov_b32_dpp v141, v110 row_ror:2 row_mask:0xf bank_mask:0xf
	s_and_saveexec_b64 s[52:53], s[6:7]
	s_xor_b64 s[52:53], exec, s[52:53]
	s_cbranch_execz .LBB0_920
	s_waitcnt vmcnt(1)
	v_pk_mul_f32 v[120:121], v[60:61], v[96:97]
	v_pk_mul_f32 v[122:123], v[58:59], v[94:95]
	v_mov_b32_e32 v142, v87
	v_mov_b32_e32 v143, v89
	s_waitcnt vmcnt(0)
	v_mov_b32_e32 v144, v91
	v_mov_b32_e32 v145, v93
	v_mov_b32_e32 v124, v123
	v_mov_b32_e32 v125, v121
	v_mov_b32_e32 v123, v120
	v_mov_b32_e32 v120, v83
	v_mov_b32_e32 v121, v85
	v_pk_fma_f32 v[140:141], v[142:143], v[140:141], v[144:145]
	v_pk_mul_f32 v[110:111], v[64:65], v[80:81]
	v_pk_fma_f32 v[120:121], v[120:121], v[138:139], v[140:141]
	v_mov_b32_e32 v138, v86
	v_mov_b32_e32 v139, v88
	v_mov_b32_e32 v140, v90
	v_mov_b32_e32 v141, v92
	v_pk_add_f32 v[120:121], v[124:125], v[120:121]
	v_mov_b32_e32 v124, v82
	v_mov_b32_e32 v125, v84
	v_pk_fma_f32 v[136:137], v[138:139], v[136:137], v[140:141]
	v_pk_mul_f32 v[114:115], v[62:63], v[78:79]
	v_pk_fma_f32 v[124:125], v[124:125], v[134:135], v[136:137]
	v_mov_b32_e32 v119, v111
	v_mul_f32_e32 v111, 0xbfb8aa3b, v121
	v_pk_add_f32 v[122:123], v[122:123], v[124:125]
	v_mov_b32_e32 v118, v115
	v_exp_f32_e32 v111, v111
	v_mul_f32_e32 v115, 0xbfb8aa3b, v123
	v_exp_f32_e32 v124, v115
	v_mov_b32_e32 v115, v110
	v_add_f32_e32 v110, 1.0, v111
	v_rcp_f32_e32 v111, v110
	v_add_f32_e32 v110, 1.0, v124
	v_rcp_f32_e32 v125, v110
	v_mul_f32_e32 v110, 0xbfb8aa3b, v120
	v_exp_f32_e32 v110, v110
	v_mov_b32_e32 v136, v67
	v_mov_b32_e32 v137, v69
	v_mov_b32_e32 v138, v75
	v_add_f32_e32 v110, 1.0, v110
	v_rcp_f32_e32 v110, v110
	v_mov_b32_e32 v139, v77
	v_mov_b32_e32 v134, v71
	v_mov_b32_e32 v135, v73
	v_pk_mul_f32 v[110:111], v[120:121], v[110:111]
	v_mul_f32_e32 v121, 0xbfb8aa3b, v122
	v_exp_f32_e32 v124, v121
	v_pk_fma_f32 v[132:133], v[136:137], v[132:133], v[138:139]
	v_mov_b32_e32 v120, v66
	v_pk_fma_f32 v[130:131], v[134:135], v[130:131], v[132:133]
	v_add_f32_e32 v124, 1.0, v124
	v_rcp_f32_e32 v124, v124
	v_pk_add_f32 v[118:119], v[118:119], v[130:131]
	v_mov_b32_e32 v121, v68
	v_mov_b32_e32 v130, v74
	v_mov_b32_e32 v131, v76
	v_pk_mul_f32 v[110:111], v[118:119], v[110:111]
	v_mov_b32_e32 v118, v70
	v_mov_b32_e32 v119, v72
	v_pk_fma_f32 v[120:121], v[120:121], v[128:129], v[130:131]
	v_add_u32_e32 v111, 0x10000, v111
	v_pk_fma_f32 v[118:119], v[118:119], v[126:127], v[120:121]
	v_add_u32_e32 v110, 0x10000, v110
	v_pk_add_f32 v[114:115], v[114:115], v[118:119]
	v_pk_mul_f32 v[118:119], v[122:123], v[124:125]
	v_and_b32_e32 v111, 0xfffe0000, v111
	v_pk_mul_f32 v[114:115], v[114:115], v[118:119]
	v_and_b32_e32 v110, 0xfffe0000, v110
	v_add_u32_e32 v114, 0x10000, v114
	v_add_u32_e32 v115, 0x10000, v115
	v_and_b32_sdwa v115, v115, s72 dst_sel:DWORD dst_unused:UNUSED_PAD src0_sel:WORD_1 src1_sel:DWORD
	v_and_b32_sdwa v114, v114, s72 dst_sel:DWORD dst_unused:UNUSED_PAD src0_sel:WORD_1 src1_sel:DWORD
	v_or_b32_e32 v111, v111, v115
	v_or_b32_e32 v110, v110, v114
	v_mov_b64_e32 v[114:115], s[20:21]
	v_mad_i64_i32 v[114:115], s[54:55], v220, s70, v[114:115]
	v_lshl_add_u64 v[114:115], v[184:185], 1, v[114:115]
	v_mov_b32_e32 v232, v238
	v_mov_b32_e32 v233, v239
	v_mov_b32_e32 v234, v110
	v_mov_b32_e32 v235, v111
	global_store_dwordx4 v[114:115], v[232:235], off
	v_mov_b32_e32 v115, v85
	v_mov_b32_e32 v114, v83
	v_mov_b32_e32 v121, v89
	v_mov_b32_e32 v120, v87
	v_mov_b32_e32 v125, v93
	v_mov_b32_e32 v124, v91
	v_mov_b32_e32 v83, v84
	v_mov_b32_e32 v87, v88
	v_mov_b32_e32 v91, v92
	v_mov_b32_e32 v111, v73
	v_mov_b32_e32 v110, v71
	v_mov_b32_e32 v119, v69
	v_mov_b32_e32 v118, v67
	v_mov_b32_e32 v123, v77
	v_mov_b32_e32 v122, v75
	v_mov_b32_e32 v71, v72
	v_mov_b32_e32 v67, v68
	v_mov_b32_e32 v75, v76

; __device__ __forceinline__ float sigmoidf_(float x) { return __builtin_amdgcn_rcpf(1.0f + __builtin_amdgcn_exp2f(-x * LOG2E)); }
; template <int CTRL> __device__ __forceinline__ float dpp_ror(float v) { return __builtin_bit_cast(float, __builtin_amdgcn_update_dpp(0, __builtin_bit_cast(int, v), CTRL, 0xf, 0xf, false)); }
;     __device__ __forceinline__ void operator()(const Acc& acc, const Unit& u, int wr, int wc, int fr, int fq) const {
;     ...
;                 for (int m = 0; m < 4; ++m) {
;                     const f32x4 ca = acc[ai][0][m][n], cg = acc[ai][1][m][n];
;                     f32x4 o;
; #pragma unroll
;                     for (int e = 0; e < 4; ++e) {
;                         const float ta1 = (fr == 15) ? pa[e] : ca[e], ta2 = (fr >= 14) ? pa[e] : ca[e], tg1 = (fr == 15) ? pg[e] : cg[e], tg2 = (fr >= 14) ? pg[e] : cg[e];
;                         const float a1 = dpp_ror<0x121>(ta1), a2 = dpp_ror<0x122>(ta2), g1 = dpp_ror<0x121>(tg1), g2 = dpp_ror<0x122>(tg2);
;                         const float va = ba[e] + wa0[e] * a2 + wa1[e] * a1 + wa2[e] * ca[e];
;                         const float vg = bg[e] + wg0[e] * g2 + wg1[e] * g1 + wg2[e] * cg[e];
;                         o[e] = vg * sigmoidf_(vg) * va;
;                     }
;                     const int row = u.pm * BM + ai * HALF + wr * 64 + m * 16 + fr;
;                     if (!(m == 0 && fr < 2)) { v2u w; w.x = pk2a(o[0], o[1]); w.y = pk2a(o[2], o[3]); *(v2u*)(ACT + (size_t)row * FF + j4) = w; }
.LBB0_922:
	s_or_b64 exec, exec, s[52:53]
	s_waitcnt vmcnt(7)
	v_cndmask_b32_e64 v68, v54, v62, s[2:3]
	s_waitcnt vmcnt(6)
	v_cndmask_b32_e64 v72, v50, v58, s[2:3]
	v_cndmask_b32_e64 v73, v50, v58, s[4:5]
	v_mov_b32_e32 v58, 0
	v_cndmask_b32_e64 v69, v54, v62, s[4:5]
	v_mov_b32_e32 v62, 0
	v_mov_b32_dpp v58, v68 row_ror:1 row_mask:0xf bank_mask:0xf
	v_mov_b32_e32 v68, 0
	v_mov_b32_dpp v62, v69 row_ror:2 row_mask:0xf bank_mask:0xf
	v_cndmask_b32_e64 v69, v55, v63, s[2:3]
	v_mov_b32_dpp v68, v72 row_ror:1 row_mask:0xf bank_mask:0xf
	v_mov_b32_e32 v72, 0
	v_cndmask_b32_e64 v63, v55, v63, s[4:5]
	s_waitcnt vmcnt(2)
	v_mov_b32_e32 v84, 0
	v_mov_b32_dpp v72, v73 row_ror:2 row_mask:0xf bank_mask:0xf
	v_cndmask_b32_e64 v73, v51, v59, s[2:3]
	v_cndmask_b32_e64 v59, v51, v59, s[4:5]
	s_waitcnt vmcnt(0)
	v_mov_b32_e32 v92, 0
	v_mov_b32_e32 v76, 0
	v_mov_b32_dpp v84, v63 row_ror:2 row_mask:0xf bank_mask:0xf
	v_mov_b32_e32 v88, 0
	v_mov_b32_dpp v92, v59 row_ror:2 row_mask:0xf bank_mask:0xf
	v_cndmask_b32_e64 v63, v56, v64, s[2:3]
	v_mov_b32_e32 v59, 0
	v_mov_b32_dpp v76, v69 row_ror:1 row_mask:0xf bank_mask:0xf
	v_mov_b32_dpp v88, v73 row_ror:1 row_mask:0xf bank_mask:0xf
	v_cndmask_b32_e64 v64, v56, v64, s[4:5]
	v_cndmask_b32_e64 v73, v52, v60, s[2:3]
	v_mov_b32_dpp v59, v63 row_ror:1 row_mask:0xf bank_mask:0xf
	v_mov_b32_e32 v63, 0
	v_mov_b32_e32 v69, 0
	v_cndmask_b32_e64 v60, v52, v60, s[4:5]
	v_mov_b32_dpp v63, v64 row_ror:2 row_mask:0xf bank_mask:0xf
	v_mov_b32_dpp v69, v73 row_ror:1 row_mask:0xf bank_mask:0xf
	v_mov_b32_e32 v73, 0
	v_cndmask_b32_e64 v64, v53, v61, s[2:3]
	v_cndmask_b32_e64 v61, v53, v61, s[4:5]
	v_mov_b32_e32 v93, 0
	v_mov_b32_dpp v73, v60 row_ror:2 row_mask:0xf bank_mask:0xf
	v_cndmask_b32_e64 v60, v57, v65, s[2:3]
	v_mov_b32_e32 v77, 0
	v_mov_b32_e32 v89, 0
	v_mov_b32_dpp v93, v61 row_ror:2 row_mask:0xf bank_mask:0xf
	v_cndmask_b32_e64 v128, v57, v65, s[4:5]
	v_mov_b32_dpp v77, v60 row_ror:1 row_mask:0xf bank_mask:0xf
	v_mov_b32_dpp v89, v64 row_ror:1 row_mask:0xf bank_mask:0xf
	v_pk_mul_f32 v[60:61], v[52:53], v[96:97]
	v_pk_mul_f32 v[64:65], v[50:51], v[94:95]
	v_pk_fma_f32 v[92:93], v[120:121], v[92:93], v[124:125]
	v_mov_b32_e32 v126, v65
	v_mov_b32_e32 v127, v61
	v_pk_fma_f32 v[88:89], v[114:115], v[88:89], v[92:93]
	v_mov_b32_e32 v65, v60
	v_pk_add_f32 v[88:89], v[126:127], v[88:89]
	v_mov_b32_e32 v85, 0
	v_mul_f32_e32 v61, 0xbfb8aa3b, v89
	v_exp_f32_e32 v92, v61
	v_pk_fma_f32 v[60:61], v[86:87], v[72:73], v[90:91]
	v_mov_b32_dpp v85, v128 row_ror:2 row_mask:0xf bank_mask:0xf
	v_pk_fma_f32 v[60:61], v[82:83], v[68:69], v[60:61]
	v_pk_mul_f32 v[72:73], v[56:57], v[80:81]
	v_pk_add_f32 v[60:61], v[64:65], v[60:61]
	v_add_f32_e32 v65, 1.0, v92
	v_mul_f32_e32 v64, 0xbfb8aa3b, v61
	v_exp_f32_e32 v64, v64
	v_mul_f32_e32 v68, 0xbfb8aa3b, v60
	v_exp_f32_e32 v68, v68
	v_rcp_f32_e32 v65, v65
	v_add_f32_e32 v64, 1.0, v64
	v_rcp_f32_e32 v69, v64
	v_mul_f32_e32 v64, 0xbfb8aa3b, v88
	v_exp_f32_e32 v64, v64
	v_add_f32_e32 v68, 1.0, v68
	v_rcp_f32_e32 v68, v68
	v_pk_mul_f32 v[92:93], v[54:55], v[78:79]
	v_add_f32_e32 v64, 1.0, v64
	v_rcp_f32_e32 v64, v64
	v_pk_fma_f32 v[84:85], v[118:119], v[84:85], v[122:123]
	v_pk_fma_f32 v[62:63], v[66:67], v[62:63], v[74:75]
	v_mov_b32_e32 v126, v93
	v_mov_b32_e32 v127, v73
	v_pk_fma_f32 v[76:77], v[110:111], v[76:77], v[84:85]
	v_mov_b32_e32 v93, v72
	v_pk_fma_f32 v[58:59], v[70:71], v[58:59], v[62:63]
	v_pk_add_f32 v[76:77], v[126:127], v[76:77]
	v_pk_mul_f32 v[64:65], v[88:89], v[64:65]
	v_pk_add_f32 v[58:59], v[92:93], v[58:59]
	v_pk_mul_f32 v[60:61], v[60:61], v[68:69]
	v_pk_mul_f32 v[64:65], v[76:77], v[64:65]
	v_pk_mul_f32 v[58:59], v[58:59], v[60:61]
	v_add_u32_e32 v60, 0x10000, v65
	v_add_u32_e32 v58, 0x10000, v58
	v_add_u32_e32 v59, 0x10000, v59
	v_add_u32_e32 v61, 0x10000, v64
	v_and_b32_e32 v60, 0xfffe0000, v60
	v_and_b32_e32 v61, 0xfffe0000, v61
	v_and_b32_sdwa v59, v59, s72 dst_sel:DWORD dst_unused:UNUSED_PAD src0_sel:WORD_1 src1_sel:DWORD
	v_and_b32_sdwa v58, v58, s72 dst_sel:DWORD dst_unused:UNUSED_PAD src0_sel:WORD_1 src1_sel:DWORD
	v_or_b32_e32 v59, v60, v59
	v_or_b32_e32 v58, v61, v58
	v_mov_b32_e32 v232, v240
	v_mov_b32_e32 v233, v241
	v_mov_b32_e32 v234, v58
	v_mov_b32_e32 v235, v59
	global_store_dwordx4 v[112:113], v[232:235], off
	v_cndmask_b32_e64 v58, v46, v54, s[2:3]
	v_cndmask_b32_e64 v60, v42, v50, s[2:3]
	v_cndmask_b32_e64 v61, v42, v50, s[4:5]
	v_mov_b32_e32 v50, 0
	v_cndmask_b32_e64 v59, v46, v54, s[4:5]
	v_mov_b32_e32 v54, 0
	v_mov_b32_dpp v50, v58 row_ror:1 row_mask:0xf bank_mask:0xf
	v_mov_b32_e32 v58, 0
	v_mov_b32_dpp v54, v59 row_ror:2 row_mask:0xf bank_mask:0xf
	v_cndmask_b32_e64 v59, v47, v55, s[2:3]
	v_mov_b32_dpp v58, v60 row_ror:1 row_mask:0xf bank_mask:0xf
	v_mov_b32_e32 v60, 0
	v_cndmask_b32_e64 v55, v47, v55, s[4:5]
	v_mov_b32_e32 v64, 0
	v_mov_b32_dpp v60, v61 row_ror:2 row_mask:0xf bank_mask:0xf
	v_cndmask_b32_e64 v61, v43, v51, s[2:3]
	v_cndmask_b32_e64 v51, v43, v51, s[4:5]
	v_mov_b32_e32 v72, 0
	v_mov_b32_e32 v62, 0
	v_mov_b32_dpp v64, v55 row_ror:2 row_mask:0xf bank_mask:0xf
	v_mov_b32_e32 v68, 0
	v_mov_b32_dpp v72, v51 row_ror:2 row_mask:0xf bank_mask:0xf
	v_cndmask_b32_e64 v55, v48, v56, s[2:3]
	v_mov_b32_e32 v51, 0
	v_mov_b32_dpp v62, v59 row_ror:1 row_mask:0xf bank_mask:0xf
	v_mov_b32_dpp v68, v61 row_ror:1 row_mask:0xf bank_mask:0xf
	v_cndmask_b32_e64 v56, v48, v56, s[4:5]
	v_cndmask_b32_e64 v61, v44, v52, s[2:3]
	v_mov_b32_dpp v51, v55 row_ror:1 row_mask:0xf bank_mask:0xf
	v_mov_b32_e32 v55, 0
	v_mov_b32_e32 v59, 0
	v_cndmask_b32_e64 v52, v44, v52, s[4:5]
	v_mov_b32_dpp v55, v56 row_ror:2 row_mask:0xf bank_mask:0xf
; __device__ __forceinline__ float sigmoidf_(float x) { return __builtin_amdgcn_rcpf(1.0f + __builtin_amdgcn_exp2f(-x * LOG2E)); }
; template <int CTRL> __device__ __forceinline__ float dpp_ror(float v) { return __builtin_bit_cast(float, __builtin_amdgcn_update_dpp(0, __builtin_bit_cast(int, v), CTRL, 0xf, 0xf, false)); }
;     __device__ __forceinline__ void operator()(const Acc& acc, const Unit& u, int wr, int wc, int fr, int fq) const {
;     ...
;                 for (int m = 0; m < 4; ++m) {
;                     const f32x4 ca = acc[ai][0][m][n], cg = acc[ai][1][m][n];
;                     f32x4 o;
; #pragma unroll
;                     for (int e = 0; e < 4; ++e) {
;                         const float ta1 = (fr == 15) ? pa[e] : ca[e], ta2 = (fr >= 14) ? pa[e] : ca[e], tg1 = (fr == 15) ? pg[e] : cg[e], tg2 = (fr >= 14) ? pg[e] : cg[e];
;                         const float a1 = dpp_ror<0x121>(ta1), a2 = dpp_ror<0x122>(ta2), g1 = dpp_ror<0x121>(tg1), g2 = dpp_ror<0x122>(tg2);
;                         const float va = ba[e] + wa0[e] * a2 + wa1[e] * a1 + wa2[e] * ca[e];
;                         const float vg = bg[e] + wg0[e] * g2 + wg1[e] * g1 + wg2[e] * cg[e];
;                         o[e] = vg * sigmoidf_(vg) * va;
;                     }
;                     const int row = u.pm * BM + ai * HALF + wr * 64 + m * 16 + fr;
;                     if (!(m == 0 && fr < 2)) { v2u w; w.x = pk2a(o[0], o[1]); w.y = pk2a(o[2], o[3]); *(v2u*)(ACT + (size_t)row * FF + j4) = w; }
;                     if ((m == 0 && fr < 2) || (m == 3 && fr >= 14)) {
	v_mov_b32_dpp v59, v61 row_ror:1 row_mask:0xf bank_mask:0xf
	v_mov_b32_e32 v61, 0
	v_cndmask_b32_e64 v56, v45, v53, s[2:3]
	v_cndmask_b32_e64 v53, v45, v53, s[4:5]
	v_mov_b32_e32 v73, 0
	v_mov_b32_dpp v61, v52 row_ror:2 row_mask:0xf bank_mask:0xf
	v_cndmask_b32_e64 v52, v49, v57, s[2:3]
	v_mov_b32_e32 v63, 0
	v_mov_b32_e32 v69, 0
	v_mov_b32_dpp v73, v53 row_ror:2 row_mask:0xf bank_mask:0xf
	v_cndmask_b32_e64 v84, v49, v57, s[4:5]
	v_mov_b32_dpp v63, v52 row_ror:1 row_mask:0xf bank_mask:0xf
	v_mov_b32_dpp v69, v56 row_ror:1 row_mask:0xf bank_mask:0xf
	v_pk_mul_f32 v[52:53], v[44:45], v[96:97]
	v_pk_mul_f32 v[56:57], v[42:43], v[94:95]
	v_pk_fma_f32 v[72:73], v[120:121], v[72:73], v[124:125]
	v_mov_b32_e32 v76, v57
	v_mov_b32_e32 v77, v53
	v_pk_fma_f32 v[68:69], v[114:115], v[68:69], v[72:73]
	v_mov_b32_e32 v57, v52
	v_pk_add_f32 v[68:69], v[76:77], v[68:69]
	v_mov_b32_e32 v65, 0
	v_mul_f32_e32 v53, 0xbfb8aa3b, v69
	v_exp_f32_e32 v72, v53
	v_pk_fma_f32 v[52:53], v[86:87], v[60:61], v[90:91]
	v_mov_b32_dpp v65, v84 row_ror:2 row_mask:0xf bank_mask:0xf
	v_pk_fma_f32 v[52:53], v[82:83], v[58:59], v[52:53]
	v_pk_mul_f32 v[60:61], v[48:49], v[80:81]
	v_pk_add_f32 v[52:53], v[56:57], v[52:53]
	v_add_f32_e32 v57, 1.0, v72
	v_mul_f32_e32 v56, 0xbfb8aa3b, v53
	v_exp_f32_e32 v56, v56
	v_mul_f32_e32 v58, 0xbfb8aa3b, v52
	v_exp_f32_e32 v58, v58
	v_rcp_f32_e32 v57, v57
	v_add_f32_e32 v56, 1.0, v56
	v_rcp_f32_e32 v59, v56
	v_mul_f32_e32 v56, 0xbfb8aa3b, v68
	v_exp_f32_e32 v56, v56
	v_add_f32_e32 v58, 1.0, v58
	v_rcp_f32_e32 v58, v58
	v_pk_mul_f32 v[72:73], v[46:47], v[78:79]
	v_add_f32_e32 v56, 1.0, v56
	v_rcp_f32_e32 v56, v56
	v_pk_fma_f32 v[64:65], v[118:119], v[64:65], v[122:123]
	v_pk_fma_f32 v[54:55], v[66:67], v[54:55], v[74:75]
	v_mov_b32_e32 v76, v73
	v_mov_b32_e32 v77, v61
	v_pk_fma_f32 v[62:63], v[110:111], v[62:63], v[64:65]
	v_mov_b32_e32 v73, v60
	v_pk_fma_f32 v[50:51], v[70:71], v[50:51], v[54:55]
	v_pk_add_f32 v[62:63], v[76:77], v[62:63]
	v_pk_mul_f32 v[56:57], v[68:69], v[56:57]
	v_pk_add_f32 v[50:51], v[72:73], v[50:51]
	v_pk_mul_f32 v[52:53], v[52:53], v[58:59]
	v_pk_mul_f32 v[56:57], v[62:63], v[56:57]
	v_pk_mul_f32 v[50:51], v[50:51], v[52:53]
	v_add_u32_e32 v52, 0x10000, v57
	v_add_u32_e32 v50, 0x10000, v50
	v_add_u32_e32 v51, 0x10000, v51
	v_add_u32_e32 v53, 0x10000, v56
	v_and_b32_e32 v52, 0xfffe0000, v52
	v_and_b32_e32 v53, 0xfffe0000, v53
	v_and_b32_sdwa v51, v51, s72 dst_sel:DWORD dst_unused:UNUSED_PAD src0_sel:WORD_1 src1_sel:DWORD
	v_and_b32_sdwa v50, v50, s72 dst_sel:DWORD dst_unused:UNUSED_PAD src0_sel:WORD_1 src1_sel:DWORD
	v_or_b32_e32 v51, v52, v51
	v_or_b32_e32 v50, v53, v50
	v_mov_b32_e32 v232, v242
	v_mov_b32_e32 v233, v243
	v_mov_b32_e32 v234, v50
	v_mov_b32_e32 v235, v51
	global_store_dwordx4 v[116:117], v[232:235], off
	v_cndmask_b32_e64 v50, v38, v46, s[2:3]
	v_cndmask_b32_e64 v52, v34, v42, s[2:3]
	v_cndmask_b32_e64 v53, v34, v42, s[4:5]
	v_mov_b32_e32 v42, 0
	v_cndmask_b32_e64 v51, v38, v46, s[4:5]
	v_mov_b32_e32 v46, 0
	v_mov_b32_dpp v42, v50 row_ror:1 row_mask:0xf bank_mask:0xf
	v_mov_b32_e32 v50, 0
	v_mov_b32_dpp v46, v51 row_ror:2 row_mask:0xf bank_mask:0xf
	v_cndmask_b32_e64 v51, v39, v47, s[2:3]
	v_mov_b32_dpp v50, v52 row_ror:1 row_mask:0xf bank_mask:0xf
	v_mov_b32_e32 v52, 0
	v_cndmask_b32_e64 v47, v39, v47, s[4:5]
	v_mov_b32_e32 v56, 0
	v_mov_b32_dpp v52, v53 row_ror:2 row_mask:0xf bank_mask:0xf
	v_cndmask_b32_e64 v53, v35, v43, s[2:3]
	v_cndmask_b32_e64 v43, v35, v43, s[4:5]
	v_mov_b32_e32 v60, 0
	v_mov_b32_e32 v54, 0
	v_mov_b32_dpp v56, v47 row_ror:2 row_mask:0xf bank_mask:0xf
	v_mov_b32_e32 v58, 0
	v_mov_b32_dpp v60, v43 row_ror:2 row_mask:0xf bank_mask:0xf
	v_cndmask_b32_e64 v47, v40, v48, s[2:3]
	v_mov_b32_e32 v43, 0
	v_mov_b32_dpp v54, v51 row_ror:1 row_mask:0xf bank_mask:0xf
	v_mov_b32_dpp v58, v53 row_ror:1 row_mask:0xf bank_mask:0xf
	v_cndmask_b32_e64 v48, v40, v48, s[4:5]
	v_cndmask_b32_e64 v53, v36, v44, s[2:3]
	v_mov_b32_dpp v43, v47 row_ror:1 row_mask:0xf bank_mask:0xf
	v_mov_b32_e32 v47, 0
	v_mov_b32_e32 v51, 0
	v_cndmask_b32_e64 v44, v36, v44, s[4:5]
	v_mov_b32_dpp v47, v48 row_ror:2 row_mask:0xf bank_mask:0xf
	v_mov_b32_dpp v51, v53 row_ror:1 row_mask:0xf bank_mask:0xf
	v_mov_b32_e32 v53, 0
	v_cndmask_b32_e64 v48, v37, v45, s[2:3]
	v_cndmask_b32_e64 v45, v37, v45, s[4:5]
	v_mov_b32_e32 v61, 0
	v_mov_b32_dpp v53, v44 row_ror:2 row_mask:0xf bank_mask:0xf
	v_cndmask_b32_e64 v44, v41, v49, s[2:3]
	v_mov_b32_e32 v55, 0
	v_mov_b32_e32 v59, 0
	v_mov_b32_dpp v61, v45 row_ror:2 row_mask:0xf bank_mask:0xf
	v_cndmask_b32_e64 v64, v41, v49, s[4:5]
	v_mov_b32_dpp v55, v44 row_ror:1 row_mask:0xf bank_mask:0xf
	v_mov_b32_dpp v59, v48 row_ror:1 row_mask:0xf bank_mask:0xf
	v_pk_mul_f32 v[44:45], v[36:37], v[96:97]
	v_pk_mul_f32 v[48:49], v[34:35], v[94:95]
	v_pk_fma_f32 v[60:61], v[120:121], v[60:61], v[124:125]
	v_mov_b32_e32 v62, v49
	v_mov_b32_e32 v63, v45
	v_pk_fma_f32 v[58:59], v[114:115], v[58:59], v[60:61]
	v_mov_b32_e32 v49, v44
	v_pk_add_f32 v[58:59], v[62:63], v[58:59]
	v_mov_b32_e32 v57, 0
	v_mul_f32_e32 v45, 0xbfb8aa3b, v59
	v_exp_f32_e32 v60, v45
	v_pk_fma_f32 v[44:45], v[86:87], v[52:53], v[90:91]
	v_mov_b32_dpp v57, v64 row_ror:2 row_mask:0xf bank_mask:0xf
	v_pk_fma_f32 v[44:45], v[82:83], v[50:51], v[44:45]
	v_pk_mul_f32 v[52:53], v[40:41], v[80:81]
	v_pk_add_f32 v[44:45], v[48:49], v[44:45]
	v_add_f32_e32 v49, 1.0, v60
	v_mul_f32_e32 v48, 0xbfb8aa3b, v45
	v_exp_f32_e32 v48, v48
	v_mul_f32_e32 v50, 0xbfb8aa3b, v44
	v_exp_f32_e32 v50, v50
	v_rcp_f32_e32 v49, v49
	v_add_f32_e32 v48, 1.0, v48
	v_rcp_f32_e32 v51, v48
	v_mul_f32_e32 v48, 0xbfb8aa3b, v58
	v_exp_f32_e32 v48, v48
	v_add_f32_e32 v50, 1.0, v50
	v_rcp_f32_e32 v50, v50
	v_pk_mul_f32 v[60:61], v[38:39], v[78:79]
	v_add_f32_e32 v48, 1.0, v48
	v_rcp_f32_e32 v48, v48
	v_pk_fma_f32 v[56:57], v[118:119], v[56:57], v[122:123]
	v_pk_fma_f32 v[46:47], v[66:67], v[46:47], v[74:75]
	v_mov_b32_e32 v62, v61
	v_mov_b32_e32 v63, v53
	v_pk_fma_f32 v[54:55], v[110:111], v[54:55], v[56:57]
	v_mov_b32_e32 v61, v52
	v_pk_fma_f32 v[42:43], v[70:71], v[42:43], v[46:47]
	v_pk_add_f32 v[54:55], v[62:63], v[54:55]
	v_pk_mul_f32 v[48:49], v[58:59], v[48:49]
	v_pk_add_f32 v[42:43], v[60:61], v[42:43]
	v_pk_mul_f32 v[44:45], v[44:45], v[50:51]
	v_pk_mul_f32 v[48:49], v[54:55], v[48:49]
	v_pk_mul_f32 v[42:43], v[42:43], v[44:45]
	v_add_u32_e32 v44, 0x10000, v49
	v_add_u32_e32 v42, 0x10000, v42
	v_add_u32_e32 v43, 0x10000, v43
	v_add_u32_e32 v45, 0x10000, v48
	v_and_b32_e32 v44, 0xfffe0000, v44
	v_and_b32_e32 v45, 0xfffe0000, v45
	v_and_b32_sdwa v43, v43, s72 dst_sel:DWORD dst_unused:UNUSED_PAD src0_sel:WORD_1 src1_sel:DWORD
	v_and_b32_sdwa v42, v42, s72 dst_sel:DWORD dst_unused:UNUSED_PAD src0_sel:WORD_1 src1_sel:DWORD
	v_or_b32_e32 v43, v44, v43
	v_or_b32_e32 v42, v45, v42
	v_mov_b32_e32 v232, v244
	v_mov_b32_e32 v233, v245
	v_mov_b32_e32 v234, v42
	v_mov_b32_e32 v235, v43
	global_store_dwordx4 v[108:109], v[232:235], off
	s_and_saveexec_b64 s[10:11], s[4:5]
	s_cbranch_execz .LBB0_924
; __device__ __forceinline__ unsigned pk2(float lo, float hi) { unsigned r; asm("v_cvt_pk_bf16_f32 %0, %1, %2" : "=v"(r) : "v"(lo), "v"(hi)); return r; }
; __device__ __forceinline__ float sigmoidf_(float x) { return __builtin_amdgcn_rcpf(1.0f + __builtin_amdgcn_exp2f(-x * LOG2E)); }
; template <int CTRL> __device__ __forceinline__ float dpp_ror(float v) { return __builtin_bit_cast(float, __builtin_amdgcn_update_dpp(0, __builtin_bit_cast(int, v), CTRL, 0xf, 0xf, false)); }
;     __device__ __forceinline__ void operator()(const Acc& acc, const Unit& u, int wr, int wc, int fr, int fq) const {
;     ...
;             for (int ai = 0; ai < 2; ++ai) {
;                 const int gi = u.pm * 4 + ai * 2 + wr;
;                 f32x4 pa = (f32x4){0.f, 0.f, 0.f, 0.f}, pg = pa;
; #pragma unroll
;                 for (int m = 0; m < 4; ++m) {
;                     const f32x4 ca = acc[ai][0][m][n], cg = acc[ai][1][m][n];
;                     f32x4 o;
; #pragma unroll
;                     for (int e = 0; e < 4; ++e) {
;                         const float ta1 = (fr == 15) ? pa[e] : ca[e], ta2 = (fr >= 14) ? pa[e] : ca[e], tg1 = (fr == 15) ? pg[e] : cg[e], tg2 = (fr >= 14) ? pg[e] : cg[e];
;                         const float a1 = dpp_ror<0x121>(ta1), a2 = dpp_ror<0x122>(ta2), g1 = dpp_ror<0x121>(tg1), g2 = dpp_ror<0x122>(tg2);
;                         const float va = ba[e] + wa0[e] * a2 + wa1[e] * a1 + wa2[e] * ca[e];
;                         const float vg = bg[e] + wg0[e] * g2 + wg1[e] * g1 + wg2[e] * cg[e];
;                         o[e] = vg * sigmoidf_(vg) * va;
;                     }
;                     const int row = u.pm * BM + ai * HALF + wr * 64 + m * 16 + fr;
;                     if (!(m == 0 && fr < 2)) { v2u w; w.x = pk2a(o[0], o[1]); w.y = pk2a(o[2], o[3]); *(v2u*)(ACT + (size_t)row * FF + j4) = w; }
;                     if ((m == 0 && fr < 2) || (m == 3 && fr >= 14)) {
;                         const int slot = (m == 0) ? fr : fr - 12;
;                         bf16* rp = RAW + ((size_t)gi * 4 + slot) * NUP + rawcol;
;                         v2u w; w.x = pk2(ca[0], ca[1]); w.y = pk2(ca[2], ca[3]); *(v2u*)rp = w;
;                         w.x = pk2(cg[0], cg[1]); w.y = pk2(cg[2], cg[3]); *(v2u*)(rp + HALF) = w;
;                     }
	v_mov_b64_e32 v[42:43], s[0:1]
	v_mad_u64_u32 v[42:43], s[52:53], v106, s71, v[42:43]
	v_mad_i32_i24 v43, v107, s71, v43
	v_lshl_add_u64 v[42:43], v[182:183], 1, v[42:43]
	v_cvt_pk_bf16_f32 v38, v38, v39
	v_cvt_pk_bf16_f32 v39, v40, v41
	global_store_dwordx2 v[42:43], v[38:39], off offset:8
	v_cvt_pk_bf16_f32 v34, v34, v35
	v_cvt_pk_bf16_f32 v35, v36, v37
	global_store_dwordx2 v[42:43], v[34:35], off offset:264
.LBB0_924:
	s_or_b64 exec, exec, s[10:11]
	v_cndmask_b32_e64 v35, v30, 0, s[2:3]
	v_mov_b32_e32 v34, 0
	v_mov_b32_e32 v36, 0
	v_mov_b32_e32 v42, 0
	v_mov_b32_dpp v34, v35 row_ror:1 row_mask:0xf bank_mask:0xf
	v_cndmask_b32_e64 v35, v30, 0, s[4:5]
	v_mov_b32_e32 v44, 0
	v_mov_b32_e32 v38, 0
	v_mov_b32_dpp v36, v35 row_ror:2 row_mask:0xf bank_mask:0xf
	v_cndmask_b32_e64 v35, v26, 0, s[2:3]
	v_mov_b32_e32 v40, 0
	v_mov_b32_e32 v46, 0
	v_mov_b32_dpp v42, v35 row_ror:1 row_mask:0xf bank_mask:0xf
	v_cndmask_b32_e64 v35, v26, 0, s[4:5]
	v_mov_b32_e32 v48, 0
	v_cndmask_b32_e64 v37, v32, 0, s[2:3]
	v_mov_b32_dpp v44, v35 row_ror:2 row_mask:0xf bank_mask:0xf
	v_cndmask_b32_e64 v35, v31, 0, s[2:3]
	v_cndmask_b32_e64 v39, v32, 0, s[4:5]
	v_mov_b32_e32 v43, 0
	v_mov_b32_dpp v38, v35 row_ror:1 row_mask:0xf bank_mask:0xf
	v_cndmask_b32_e64 v35, v31, 0, s[4:5]
	v_mov_b32_e32 v45, 0
	v_cndmask_b32_e64 v41, v33, 0, s[2:3]
	v_mov_b32_dpp v40, v35 row_ror:2 row_mask:0xf bank_mask:0xf
	v_cndmask_b32_e64 v35, v27, 0, s[2:3]
	v_cndmask_b32_e64 v47, v33, 0, s[4:5]
	v_cndmask_b32_e64 v49, v29, 0, s[2:3]
	v_mov_b32_dpp v46, v35 row_ror:1 row_mask:0xf bank_mask:0xf
	v_cndmask_b32_e64 v35, v27, 0, s[4:5]
	v_cndmask_b32_e64 v50, v29, 0, s[4:5]
	s_nop 0
	v_mov_b32_dpp v48, v35 row_ror:2 row_mask:0xf bank_mask:0xf
	v_mov_b32_e32 v35, 0
	s_nop 1
	v_mov_b32_dpp v35, v37 row_ror:1 row_mask:0xf bank_mask:0xf
	v_mov_b32_e32 v37, 0
	s_nop 1
	v_mov_b32_dpp v37, v39 row_ror:2 row_mask:0xf bank_mask:0xf
	v_cndmask_b32_e64 v39, v28, 0, s[2:3]
	s_nop 1
	v_mov_b32_dpp v43, v39 row_ror:1 row_mask:0xf bank_mask:0xf
	v_cndmask_b32_e64 v39, v28, 0, s[4:5]
	s_nop 1
	v_mov_b32_dpp v45, v39 row_ror:2 row_mask:0xf bank_mask:0xf
	v_mov_b32_e32 v39, 0
	s_nop 1
	v_mov_b32_dpp v39, v41 row_ror:1 row_mask:0xf bank_mask:0xf
	v_mov_b32_e32 v41, 0
	s_nop 1
	v_mov_b32_dpp v41, v47 row_ror:2 row_mask:0xf bank_mask:0xf
	v_mov_b32_e32 v47, 0
	s_nop 1
	v_mov_b32_dpp v47, v49 row_ror:1 row_mask:0xf bank_mask:0xf
	v_mov_b32_e32 v49, 0
	s_nop 1
	v_mov_b32_dpp v49, v50 row_ror:2 row_mask:0xf bank_mask:0xf
	s_and_saveexec_b64 s[10:11], s[6:7]
	s_xor_b64 s[10:11], exec, s[10:11]
	s_cbranch_execz .LBB0_926
	v_pk_mul_f32 v[56:57], v[28:29], v[96:97]
	v_pk_mul_f32 v[58:59], v[26:27], v[94:95]
	v_pk_fma_f32 v[48:49], v[120:121], v[48:49], v[124:125]
	v_mov_b32_e32 v60, v59
	v_mov_b32_e32 v61, v57
	v_pk_fma_f32 v[46:47], v[114:115], v[46:47], v[48:49]
	v_pk_fma_f32 v[44:45], v[86:87], v[44:45], v[90:91]
	v_pk_add_f32 v[46:47], v[60:61], v[46:47]
	v_mov_b32_e32 v59, v56
	v_mul_f32_e32 v48, 0xbfb8aa3b, v47
	v_exp_f32_e32 v48, v48
	v_pk_fma_f32 v[42:43], v[82:83], v[42:43], v[44:45]
	v_pk_fma_f32 v[40:41], v[118:119], v[40:41], v[122:123]
	v_pk_add_f32 v[42:43], v[58:59], v[42:43]
	v_add_f32_e32 v45, 1.0, v48
	v_mul_f32_e32 v44, 0xbfb8aa3b, v43
	v_mul_f32_e32 v48, 0xbfb8aa3b, v46
	v_exp_f32_e32 v44, v44
	v_exp_f32_e32 v48, v48
	v_pk_fma_f32 v[38:39], v[110:111], v[38:39], v[40:41]
	v_rcp_f32_e32 v45, v45
	v_add_f32_e32 v44, 1.0, v44
	v_add_f32_e32 v40, 1.0, v48
	v_rcp_f32_e32 v49, v44
	v_rcp_f32_e32 v44, v40
	v_mul_f32_e32 v40, 0xbfb8aa3b, v42
	v_exp_f32_e32 v48, v40
	v_pk_mul_f32 v[50:51], v[32:33], v[80:81]
	v_pk_mul_f32 v[52:53], v[30:31], v[78:79]
	v_mov_b32_e32 v55, v51
	v_mov_b32_e32 v54, v53
	v_pk_add_f32 v[38:39], v[54:55], v[38:39]
	v_pk_mul_f32 v[40:41], v[46:47], v[44:45]
	v_pk_fma_f32 v[36:37], v[66:67], v[36:37], v[74:75]
	v_pk_mul_f32 v[38:39], v[38:39], v[40:41]
	v_add_f32_e32 v40, 1.0, v48
	v_rcp_f32_e32 v48, v40
	v_mov_b32_e32 v53, v50
	v_pk_fma_f32 v[34:35], v[70:71], v[34:35], v[36:37]
	v_pk_mul_f32 v[36:37], v[42:43], v[48:49]
	v_pk_add_f32 v[34:35], v[52:53], v[34:35]
	s_nop 0
	v_pk_mul_f32 v[34:35], v[34:35], v[36:37]
	v_add_u32_e32 v36, 0x10000, v39
	v_add_u32_e32 v34, 0x10000, v34
	v_add_u32_e32 v35, 0x10000, v35
	v_add_u32_e32 v37, 0x10000, v38
	v_and_b32_e32 v36, 0xfffe0000, v36
	v_and_b32_e32 v37, 0xfffe0000, v37
	v_and_b32_sdwa v35, v35, s72 dst_sel:DWORD dst_unused:UNUSED_PAD src0_sel:WORD_1 src1_sel:DWORD
	v_and_b32_sdwa v34, v34, s72 dst_sel:DWORD dst_unused:UNUSED_PAD src0_sel:WORD_1 src1_sel:DWORD
	v_or_b32_e32 v35, v36, v35
	v_or_b32_e32 v34, v37, v34
	v_mov_b64_e32 v[36:37], s[20:21]
	v_mad_i64_i32 v[36:37], s[52:53], v146, s70, v[36:37]
	v_lshl_add_u64 v[36:37], v[184:185], 1, v[36:37]
	v_mov_b32_e32 v232, v246
	v_mov_b32_e32 v233, v247
	v_mov_b32_e32 v234, v34
	v_mov_b32_e32 v235, v35
	global_store_dwordx4 v[36:37], v[232:235], off

; __device__ __forceinline__ float sigmoidf_(float x) { return __builtin_amdgcn_rcpf(1.0f + __builtin_amdgcn_exp2f(-x * LOG2E)); }
; template <int CTRL> __device__ __forceinline__ float dpp_ror(float v) { return __builtin_bit_cast(float, __builtin_amdgcn_update_dpp(0, __builtin_bit_cast(int, v), CTRL, 0xf, 0xf, false)); }
;     __device__ __forceinline__ void operator()(const Acc& acc, const Unit& u, int wr, int wc, int fr, int fq) const {
;     ...
;                 for (int m = 0; m < 4; ++m) {
;                     const f32x4 ca = acc[ai][0][m][n], cg = acc[ai][1][m][n];
;                     f32x4 o;
; #pragma unroll
;                     for (int e = 0; e < 4; ++e) {
;                         const float ta1 = (fr == 15) ? pa[e] : ca[e], ta2 = (fr >= 14) ? pa[e] : ca[e], tg1 = (fr == 15) ? pg[e] : cg[e], tg2 = (fr >= 14) ? pg[e] : cg[e];
;                         const float a1 = dpp_ror<0x121>(ta1), a2 = dpp_ror<0x122>(ta2), g1 = dpp_ror<0x121>(tg1), g2 = dpp_ror<0x122>(tg2);
;                         const float va = ba[e] + wa0[e] * a2 + wa1[e] * a1 + wa2[e] * ca[e];
;                         const float vg = bg[e] + wg0[e] * g2 + wg1[e] * g1 + wg2[e] * cg[e];
;                         o[e] = vg * sigmoidf_(vg) * va;
;                     }
;                     const int row = u.pm * BM + ai * HALF + wr * 64 + m * 16 + fr;
;                     if (!(m == 0 && fr < 2)) { v2u w; w.x = pk2a(o[0], o[1]); w.y = pk2a(o[2], o[3]); *(v2u*)(ACT + (size_t)row * FF + j4) = w; }
.LBB0_928:
	s_or_b64 exec, exec, s[10:11]
	v_cndmask_b32_e64 v34, v22, v30, s[2:3]
	v_cndmask_b32_e64 v36, v18, v26, s[2:3]
	v_cndmask_b32_e64 v37, v18, v26, s[4:5]
	v_mov_b32_e32 v26, 0
	v_cndmask_b32_e64 v35, v22, v30, s[4:5]
	v_mov_b32_e32 v30, 0
	v_mov_b32_dpp v26, v34 row_ror:1 row_mask:0xf bank_mask:0xf
	v_mov_b32_e32 v34, 0
	v_mov_b32_dpp v30, v35 row_ror:2 row_mask:0xf bank_mask:0xf
	v_cndmask_b32_e64 v35, v23, v31, s[2:3]
	v_mov_b32_dpp v34, v36 row_ror:1 row_mask:0xf bank_mask:0xf
	v_mov_b32_e32 v36, 0
	v_cndmask_b32_e64 v31, v23, v31, s[4:5]
	v_mov_b32_e32 v40, 0
	v_mov_b32_dpp v36, v37 row_ror:2 row_mask:0xf bank_mask:0xf
	v_cndmask_b32_e64 v37, v19, v27, s[2:3]
	v_cndmask_b32_e64 v27, v19, v27, s[4:5]
	v_mov_b32_e32 v44, 0
	v_mov_b32_e32 v38, 0
	v_mov_b32_dpp v40, v31 row_ror:2 row_mask:0xf bank_mask:0xf
	v_mov_b32_e32 v42, 0
	v_mov_b32_dpp v44, v27 row_ror:2 row_mask:0xf bank_mask:0xf
	v_cndmask_b32_e64 v31, v24, v32, s[2:3]
	v_mov_b32_e32 v27, 0
	v_mov_b32_dpp v38, v35 row_ror:1 row_mask:0xf bank_mask:0xf
	v_mov_b32_dpp v42, v37 row_ror:1 row_mask:0xf bank_mask:0xf
	v_cndmask_b32_e64 v32, v24, v32, s[4:5]
	v_cndmask_b32_e64 v37, v20, v28, s[2:3]
	v_mov_b32_dpp v27, v31 row_ror:1 row_mask:0xf bank_mask:0xf
	v_mov_b32_e32 v31, 0
	v_mov_b32_e32 v35, 0
	v_cndmask_b32_e64 v28, v20, v28, s[4:5]
	v_mov_b32_dpp v31, v32 row_ror:2 row_mask:0xf bank_mask:0xf
	v_mov_b32_dpp v35, v37 row_ror:1 row_mask:0xf bank_mask:0xf
	v_mov_b32_e32 v37, 0
	v_cndmask_b32_e64 v32, v21, v29, s[2:3]
	v_cndmask_b32_e64 v29, v21, v29, s[4:5]
	v_mov_b32_e32 v45, 0
	v_mov_b32_dpp v37, v28 row_ror:2 row_mask:0xf bank_mask:0xf
	v_cndmask_b32_e64 v28, v25, v33, s[2:3]
	v_mov_b32_e32 v39, 0
	v_mov_b32_e32 v43, 0
	v_mov_b32_dpp v45, v29 row_ror:2 row_mask:0xf bank_mask:0xf
	v_cndmask_b32_e64 v48, v25, v33, s[4:5]
	v_mov_b32_dpp v39, v28 row_ror:1 row_mask:0xf bank_mask:0xf
	v_mov_b32_dpp v43, v32 row_ror:1 row_mask:0xf bank_mask:0xf
	v_pk_mul_f32 v[28:29], v[20:21], v[96:97]
	v_pk_mul_f32 v[32:33], v[18:19], v[94:95]
	v_pk_fma_f32 v[44:45], v[120:121], v[44:45], v[124:125]
	v_mov_b32_e32 v46, v33
	v_mov_b32_e32 v47, v29
	v_pk_fma_f32 v[42:43], v[114:115], v[42:43], v[44:45]
	v_mov_b32_e32 v33, v28
	v_pk_add_f32 v[42:43], v[46:47], v[42:43]
	v_mov_b32_e32 v41, 0
	v_mul_f32_e32 v29, 0xbfb8aa3b, v43
	v_exp_f32_e32 v44, v29
	v_pk_fma_f32 v[28:29], v[86:87], v[36:37], v[90:91]
	v_mov_b32_dpp v41, v48 row_ror:2 row_mask:0xf bank_mask:0xf
	v_pk_fma_f32 v[28:29], v[82:83], v[34:35], v[28:29]
	v_pk_mul_f32 v[36:37], v[24:25], v[80:81]
	v_pk_add_f32 v[28:29], v[32:33], v[28:29]
	v_add_f32_e32 v33, 1.0, v44
	v_mul_f32_e32 v32, 0xbfb8aa3b, v29
	v_exp_f32_e32 v32, v32
	v_mul_f32_e32 v34, 0xbfb8aa3b, v28
	v_exp_f32_e32 v34, v34
	v_rcp_f32_e32 v33, v33
	v_add_f32_e32 v32, 1.0, v32
	v_rcp_f32_e32 v35, v32
	v_mul_f32_e32 v32, 0xbfb8aa3b, v42
	v_exp_f32_e32 v32, v32
	v_add_f32_e32 v34, 1.0, v34
	v_rcp_f32_e32 v34, v34
	v_pk_mul_f32 v[44:45], v[22:23], v[78:79]
	v_add_f32_e32 v32, 1.0, v32
	v_rcp_f32_e32 v32, v32
	v_pk_fma_f32 v[40:41], v[118:119], v[40:41], v[122:123]
	v_pk_fma_f32 v[30:31], v[66:67], v[30:31], v[74:75]
	v_mov_b32_e32 v46, v45
	v_mov_b32_e32 v47, v37
	v_pk_fma_f32 v[38:39], v[110:111], v[38:39], v[40:41]
	v_mov_b32_e32 v45, v36
	v_pk_fma_f32 v[26:27], v[70:71], v[26:27], v[30:31]
	v_pk_add_f32 v[38:39], v[46:47], v[38:39]
	v_pk_mul_f32 v[32:33], v[42:43], v[32:33]
	v_pk_add_f32 v[26:27], v[44:45], v[26:27]
	v_pk_mul_f32 v[28:29], v[28:29], v[34:35]
	v_pk_mul_f32 v[32:33], v[38:39], v[32:33]
	v_pk_mul_f32 v[26:27], v[26:27], v[28:29]
	v_add_u32_e32 v28, 0x10000, v33
	v_add_u32_e32 v26, 0x10000, v26
	v_add_u32_e32 v27, 0x10000, v27
	v_add_u32_e32 v29, 0x10000, v32
	v_and_b32_e32 v28, 0xfffe0000, v28
	v_and_b32_e32 v29, 0xfffe0000, v29
	v_and_b32_sdwa v27, v27, s72 dst_sel:DWORD dst_unused:UNUSED_PAD src0_sel:WORD_1 src1_sel:DWORD
	v_and_b32_sdwa v26, v26, s72 dst_sel:DWORD dst_unused:UNUSED_PAD src0_sel:WORD_1 src1_sel:DWORD
	v_or_b32_e32 v27, v28, v27
	v_or_b32_e32 v26, v29, v26
	v_mov_b32_e32 v232, v248
	v_mov_b32_e32 v233, v249
	v_mov_b32_e32 v234, v26
	v_mov_b32_e32 v235, v27
	global_store_dwordx4 v[100:101], v[232:235], off
	v_cndmask_b32_e64 v26, v14, v22, s[2:3]
	v_cndmask_b32_e64 v28, v10, v18, s[2:3]
	v_cndmask_b32_e64 v29, v10, v18, s[4:5]
	v_mov_b32_e32 v18, 0
	v_cndmask_b32_e64 v27, v14, v22, s[4:5]
	v_mov_b32_e32 v22, 0
	v_mov_b32_dpp v18, v26 row_ror:1 row_mask:0xf bank_mask:0xf
	v_mov_b32_e32 v26, 0
	v_mov_b32_dpp v22, v27 row_ror:2 row_mask:0xf bank_mask:0xf
	v_cndmask_b32_e64 v27, v15, v23, s[2:3]
	v_mov_b32_dpp v26, v28 row_ror:1 row_mask:0xf bank_mask:0xf
	v_mov_b32_e32 v28, 0
	v_cndmask_b32_e64 v23, v15, v23, s[4:5]
	v_mov_b32_e32 v32, 0
	v_mov_b32_dpp v28, v29 row_ror:2 row_mask:0xf bank_mask:0xf
	v_cndmask_b32_e64 v29, v11, v19, s[2:3]
	v_cndmask_b32_e64 v19, v11, v19, s[4:5]
	v_mov_b32_e32 v36, 0
	v_mov_b32_e32 v30, 0
	v_mov_b32_dpp v32, v23 row_ror:2 row_mask:0xf bank_mask:0xf
	v_mov_b32_e32 v34, 0
	v_mov_b32_dpp v36, v19 row_ror:2 row_mask:0xf bank_mask:0xf
	v_cndmask_b32_e64 v23, v16, v24, s[2:3]
	v_mov_b32_e32 v19, 0
	v_mov_b32_dpp v30, v27 row_ror:1 row_mask:0xf bank_mask:0xf
	v_mov_b32_dpp v34, v29 row_ror:1 row_mask:0xf bank_mask:0xf
	v_cndmask_b32_e64 v24, v16, v24, s[4:5]
	v_cndmask_b32_e64 v29, v12, v20, s[2:3]
	v_mov_b32_dpp v19, v23 row_ror:1 row_mask:0xf bank_mask:0xf
	v_mov_b32_e32 v23, 0
	v_mov_b32_e32 v27, 0
	v_cndmask_b32_e64 v20, v12, v20, s[4:5]
	v_mov_b32_dpp v23, v24 row_ror:2 row_mask:0xf bank_mask:0xf
	v_mov_b32_dpp v27, v29 row_ror:1 row_mask:0xf bank_mask:0xf
	v_mov_b32_e32 v29, 0
	v_cndmask_b32_e64 v24, v13, v21, s[2:3]
; __device__ __forceinline__ float sigmoidf_(float x) { return __builtin_amdgcn_rcpf(1.0f + __builtin_amdgcn_exp2f(-x * LOG2E)); }
; template <int CTRL> __device__ __forceinline__ float dpp_ror(float v) { return __builtin_bit_cast(float, __builtin_amdgcn_update_dpp(0, __builtin_bit_cast(int, v), CTRL, 0xf, 0xf, false)); }
;     __device__ __forceinline__ void operator()(const Acc& acc, const Unit& u, int wr, int wc, int fr, int fq) const {
;     ...
;                 for (int m = 0; m < 4; ++m) {
;                     const f32x4 ca = acc[ai][0][m][n], cg = acc[ai][1][m][n];
;                     f32x4 o;
; #pragma unroll
;                     for (int e = 0; e < 4; ++e) {
;                         const float ta1 = (fr == 15) ? pa[e] : ca[e], ta2 = (fr >= 14) ? pa[e] : ca[e], tg1 = (fr == 15) ? pg[e] : cg[e], tg2 = (fr >= 14) ? pg[e] : cg[e];
;                         const float a1 = dpp_ror<0x121>(ta1), a2 = dpp_ror<0x122>(ta2), g1 = dpp_ror<0x121>(tg1), g2 = dpp_ror<0x122>(tg2);
;                         const float va = ba[e] + wa0[e] * a2 + wa1[e] * a1 + wa2[e] * ca[e];
;                         const float vg = bg[e] + wg0[e] * g2 + wg1[e] * g1 + wg2[e] * cg[e];
;                         o[e] = vg * sigmoidf_(vg) * va;
;                     }
;                     const int row = u.pm * BM + ai * HALF + wr * 64 + m * 16 + fr;
;                     if (!(m == 0 && fr < 2)) { v2u w; w.x = pk2a(o[0], o[1]); w.y = pk2a(o[2], o[3]); *(v2u*)(ACT + (size_t)row * FF + j4) = w; }
;                     if ((m == 0 && fr < 2) || (m == 3 && fr >= 14)) {
	v_cndmask_b32_e64 v21, v13, v21, s[4:5]
	v_mov_b32_e32 v37, 0
	v_mov_b32_dpp v29, v20 row_ror:2 row_mask:0xf bank_mask:0xf
	v_cndmask_b32_e64 v20, v17, v25, s[2:3]
	v_mov_b32_e32 v31, 0
	v_mov_b32_e32 v35, 0
	v_mov_b32_dpp v37, v21 row_ror:2 row_mask:0xf bank_mask:0xf
	v_cndmask_b32_e64 v40, v17, v25, s[4:5]
	v_mov_b32_dpp v31, v20 row_ror:1 row_mask:0xf bank_mask:0xf
	v_mov_b32_dpp v35, v24 row_ror:1 row_mask:0xf bank_mask:0xf
	v_pk_mul_f32 v[20:21], v[12:13], v[96:97]
	v_pk_mul_f32 v[24:25], v[10:11], v[94:95]
	v_pk_fma_f32 v[36:37], v[120:121], v[36:37], v[124:125]
	v_mov_b32_e32 v38, v25
	v_mov_b32_e32 v39, v21
	v_pk_fma_f32 v[34:35], v[114:115], v[34:35], v[36:37]
	v_mov_b32_e32 v25, v20
	v_pk_add_f32 v[34:35], v[38:39], v[34:35]
	v_mov_b32_e32 v33, 0
	v_mul_f32_e32 v21, 0xbfb8aa3b, v35
	v_exp_f32_e32 v36, v21
	v_pk_fma_f32 v[20:21], v[86:87], v[28:29], v[90:91]
	v_mov_b32_dpp v33, v40 row_ror:2 row_mask:0xf bank_mask:0xf
	v_pk_fma_f32 v[20:21], v[82:83], v[26:27], v[20:21]
	v_pk_mul_f32 v[28:29], v[16:17], v[80:81]
	v_pk_add_f32 v[20:21], v[24:25], v[20:21]
	v_add_f32_e32 v25, 1.0, v36
	v_mul_f32_e32 v24, 0xbfb8aa3b, v21
	v_exp_f32_e32 v24, v24
	v_mul_f32_e32 v26, 0xbfb8aa3b, v20
	v_exp_f32_e32 v26, v26
	v_rcp_f32_e32 v25, v25
	v_add_f32_e32 v24, 1.0, v24
	v_rcp_f32_e32 v27, v24
	v_mul_f32_e32 v24, 0xbfb8aa3b, v34
	v_exp_f32_e32 v24, v24
	v_add_f32_e32 v26, 1.0, v26
	v_rcp_f32_e32 v26, v26
	v_pk_mul_f32 v[36:37], v[14:15], v[78:79]
	v_add_f32_e32 v24, 1.0, v24
	v_rcp_f32_e32 v24, v24
	v_pk_fma_f32 v[32:33], v[118:119], v[32:33], v[122:123]
	v_pk_fma_f32 v[22:23], v[66:67], v[22:23], v[74:75]
	v_mov_b32_e32 v38, v37
	v_mov_b32_e32 v39, v29
	v_pk_fma_f32 v[30:31], v[110:111], v[30:31], v[32:33]
	v_mov_b32_e32 v37, v28
	v_pk_fma_f32 v[18:19], v[70:71], v[18:19], v[22:23]
	v_pk_add_f32 v[30:31], v[38:39], v[30:31]
	v_pk_mul_f32 v[24:25], v[34:35], v[24:25]
	v_pk_add_f32 v[18:19], v[36:37], v[18:19]
	v_pk_mul_f32 v[20:21], v[20:21], v[26:27]
	v_pk_mul_f32 v[24:25], v[30:31], v[24:25]
	v_pk_mul_f32 v[18:19], v[18:19], v[20:21]
	v_add_u32_e32 v20, 0x10000, v25
	v_add_u32_e32 v18, 0x10000, v18
	v_add_u32_e32 v19, 0x10000, v19
	v_add_u32_e32 v21, 0x10000, v24
	v_and_b32_e32 v20, 0xfffe0000, v20
	v_and_b32_e32 v21, 0xfffe0000, v21
	v_and_b32_sdwa v19, v19, s72 dst_sel:DWORD dst_unused:UNUSED_PAD src0_sel:WORD_1 src1_sel:DWORD
	v_and_b32_sdwa v18, v18, s72 dst_sel:DWORD dst_unused:UNUSED_PAD src0_sel:WORD_1 src1_sel:DWORD
	v_or_b32_e32 v19, v20, v19
	v_or_b32_e32 v18, v21, v18
	v_mov_b32_e32 v232, v250
	v_mov_b32_e32 v233, v251
	v_mov_b32_e32 v234, v18
	v_mov_b32_e32 v235, v19
	global_store_dwordx4 v[102:103], v[232:235], off
	v_cndmask_b32_e64 v18, v6, v14, s[2:3]
	v_cndmask_b32_e64 v20, v2, v10, s[2:3]
	v_cndmask_b32_e64 v21, v2, v10, s[4:5]
	v_mov_b32_e32 v10, 0
	v_cndmask_b32_e64 v19, v6, v14, s[4:5]
	v_mov_b32_e32 v14, 0
	v_mov_b32_dpp v10, v18 row_ror:1 row_mask:0xf bank_mask:0xf
	v_mov_b32_e32 v18, 0
	v_mov_b32_dpp v14, v19 row_ror:2 row_mask:0xf bank_mask:0xf
	v_cndmask_b32_e64 v19, v7, v15, s[2:3]
	v_mov_b32_dpp v18, v20 row_ror:1 row_mask:0xf bank_mask:0xf
	v_mov_b32_e32 v20, 0
	v_cndmask_b32_e64 v15, v7, v15, s[4:5]
	v_mov_b32_e32 v24, 0
	v_mov_b32_dpp v20, v21 row_ror:2 row_mask:0xf bank_mask:0xf
	v_cndmask_b32_e64 v21, v3, v11, s[2:3]
	v_cndmask_b32_e64 v11, v3, v11, s[4:5]
	v_mov_b32_e32 v28, 0
	v_mov_b32_e32 v22, 0
	v_mov_b32_dpp v24, v15 row_ror:2 row_mask:0xf bank_mask:0xf
	v_mov_b32_e32 v26, 0
	v_mov_b32_dpp v28, v11 row_ror:2 row_mask:0xf bank_mask:0xf
	v_cndmask_b32_e64 v15, v8, v16, s[2:3]
	v_mov_b32_e32 v11, 0
	v_mov_b32_dpp v22, v19 row_ror:1 row_mask:0xf bank_mask:0xf
	v_mov_b32_dpp v26, v21 row_ror:1 row_mask:0xf bank_mask:0xf
	v_cndmask_b32_e64 v16, v8, v16, s[4:5]
	v_cndmask_b32_e64 v21, v4, v12, s[2:3]
	v_mov_b32_dpp v11, v15 row_ror:1 row_mask:0xf bank_mask:0xf
	v_mov_b32_e32 v15, 0
	v_mov_b32_e32 v19, 0
	v_cndmask_b32_e64 v12, v4, v12, s[4:5]
	v_mov_b32_dpp v15, v16 row_ror:2 row_mask:0xf bank_mask:0xf
	v_mov_b32_dpp v19, v21 row_ror:1 row_mask:0xf bank_mask:0xf
	v_mov_b32_e32 v21, 0
	v_cndmask_b32_e64 v16, v5, v13, s[2:3]
	v_cndmask_b32_e64 v13, v5, v13, s[4:5]
	v_mov_b32_e32 v29, 0
	v_mov_b32_dpp v21, v12 row_ror:2 row_mask:0xf bank_mask:0xf
	v_cndmask_b32_e64 v12, v9, v17, s[2:3]
	v_mov_b32_e32 v23, 0
	v_mov_b32_e32 v27, 0
	v_mov_b32_dpp v29, v13 row_ror:2 row_mask:0xf bank_mask:0xf
	v_cndmask_b32_e64 v32, v9, v17, s[4:5]
	v_mov_b32_dpp v23, v12 row_ror:1 row_mask:0xf bank_mask:0xf
	v_mov_b32_dpp v27, v16 row_ror:1 row_mask:0xf bank_mask:0xf
	v_pk_mul_f32 v[12:13], v[4:5], v[96:97]
	v_pk_mul_f32 v[16:17], v[2:3], v[94:95]
	v_pk_fma_f32 v[28:29], v[120:121], v[28:29], v[124:125]
	v_mov_b32_e32 v30, v17
	v_mov_b32_e32 v31, v13
	v_pk_fma_f32 v[26:27], v[114:115], v[26:27], v[28:29]
	v_mov_b32_e32 v17, v12
	v_pk_add_f32 v[26:27], v[30:31], v[26:27]
	v_mov_b32_e32 v25, 0
	v_mul_f32_e32 v13, 0xbfb8aa3b, v27
	v_exp_f32_e32 v28, v13
	v_pk_fma_f32 v[12:13], v[86:87], v[20:21], v[90:91]
	v_mov_b32_dpp v25, v32 row_ror:2 row_mask:0xf bank_mask:0xf
	v_pk_fma_f32 v[12:13], v[82:83], v[18:19], v[12:13]
	v_pk_mul_f32 v[20:21], v[8:9], v[80:81]
	v_pk_add_f32 v[12:13], v[16:17], v[12:13]
	v_add_f32_e32 v17, 1.0, v28
	v_mul_f32_e32 v16, 0xbfb8aa3b, v12
	v_exp_f32_e32 v16, v16
	v_mul_f32_e32 v19, 0xbfb8aa3b, v13
	v_exp_f32_e32 v19, v19
	v_rcp_f32_e32 v17, v17
	v_add_f32_e32 v16, 1.0, v16
	v_rcp_f32_e32 v18, v16
	v_mul_f32_e32 v16, 0xbfb8aa3b, v26
	v_exp_f32_e32 v16, v16
	v_add_f32_e32 v19, 1.0, v19
	v_rcp_f32_e32 v19, v19
	v_pk_mul_f32 v[28:29], v[6:7], v[78:79]
	v_add_f32_e32 v16, 1.0, v16
	v_rcp_f32_e32 v16, v16
	v_pk_fma_f32 v[24:25], v[118:119], v[24:25], v[122:123]
	v_pk_fma_f32 v[14:15], v[66:67], v[14:15], v[74:75]
	v_mov_b32_e32 v30, v29
	v_mov_b32_e32 v31, v21
	v_pk_fma_f32 v[22:23], v[110:111], v[22:23], v[24:25]
	v_mov_b32_e32 v29, v20
	v_pk_fma_f32 v[10:11], v[70:71], v[10:11], v[14:15]
	v_pk_add_f32 v[22:23], v[30:31], v[22:23]
	v_pk_mul_f32 v[16:17], v[26:27], v[16:17]
	v_pk_add_f32 v[10:11], v[28:29], v[10:11]
	v_pk_mul_f32 v[12:13], v[12:13], v[18:19]
	v_pk_mul_f32 v[16:17], v[22:23], v[16:17]
	v_pk_mul_f32 v[10:11], v[10:11], v[12:13]
	v_add_u32_e32 v12, 0x10000, v17
	v_add_u32_e32 v10, 0x10000, v10
	v_add_u32_e32 v11, 0x10000, v11
	v_add_u32_e32 v13, 0x10000, v16
	v_and_b32_e32 v12, 0xfffe0000, v12
	v_and_b32_e32 v13, 0xfffe0000, v13
	v_and_b32_sdwa v11, v11, s72 dst_sel:DWORD dst_unused:UNUSED_PAD src0_sel:WORD_1 src1_sel:DWORD
	v_and_b32_sdwa v10, v10, s72 dst_sel:DWORD dst_unused:UNUSED_PAD src0_sel:WORD_1 src1_sel:DWORD
	v_or_b32_e32 v11, v12, v11
	v_or_b32_e32 v10, v13, v10
	v_mov_b32_e32 v232, v254
	v_mov_b32_e32 v233, v255
	v_mov_b32_e32 v234, v10
	v_mov_b32_e32 v235, v11
	global_store_dwordx4 v[104:105], v[232:235], off
	s_and_saveexec_b64 s[10:11], s[4:5]
	s_cbranch_execz .LBB0_930
; __device__ __forceinline__ unsigned pk2(float lo, float hi) { unsigned r; asm("v_cvt_pk_bf16_f32 %0, %1, %2" : "=v"(r) : "v"(lo), "v"(hi)); return r; }
;     __device__ __forceinline__ void operator()(const Acc& acc, const Unit& u, int wr, int wc, int fr, int fq) const {
;     ...
;                     if ((m == 0 && fr < 2) || (m == 3 && fr >= 14)) {
;                         const int slot = (m == 0) ? fr : fr - 12;
;                         bf16* rp = RAW + ((size_t)gi * 4 + slot) * NUP + rawcol;
;                         v2u w; w.x = pk2(ca[0], ca[1]); w.y = pk2(ca[2], ca[3]); *(v2u*)rp = w;
;                         w.x = pk2(cg[0], cg[1]); w.y = pk2(cg[2], cg[3]); *(v2u*)(rp + HALF) = w;
;                     }
	v_mov_b64_e32 v[10:11], s[0:1]
	v_mad_u64_u32 v[10:11], s[12:13], v98, s71, v[10:11]
	v_mad_i32_i24 v11, v99, s71, v11
	v_lshl_add_u64 v[10:11], v[182:183], 1, v[10:11]
	v_cvt_pk_bf16_f32 v6, v6, v7
	v_cvt_pk_bf16_f32 v7, v8, v9
	global_store_dwordx2 v[10:11], v[6:7], off offset:8
	v_cvt_pk_bf16_f32 v2, v2, v3
	v_cvt_pk_bf16_f32 v3, v4, v5
	global_store_dwordx2 v[10:11], v[2:3], off offset:264
